# v26 with the projection-output stores back to the default cache policy (no nt)
# speedup vs baseline: 1.0062x; 1.0062x over previous
.LBB0_664:
	s_bitcmp0_b32 s15, 2
	s_cselect_b64 s[0:1], -1, 0
	v_cndmask_b32_e64 v182, v192, 1.0, s[0:1]
	v_pk_mul_f32 v[150:151], v[182:183], v[150:151] op_sel_hi:[0,1]
	s_lshl_b32 s0, s14, 6
	v_pk_mul_f32 v[194:195], v[182:183], v[148:149] op_sel_hi:[0,1]
	v_pk_mul_f32 v[148:149], v[182:183], v[146:147] op_sel_hi:[0,1]
	v_cvt_pk_bf16_f32 v146, v150, v151
	v_mov_b64_e32 v[150:151], s[22:23]
	s_ashr_i32 s1, s0, 31
	v_mad_i64_i32 v[150:151], s[14:15], v180, s60, v[150:151]
	v_lshl_add_u64 v[150:151], s[0:1], 1, v[150:151]
	v_lshlrev_b32_e32 v162, 1, v164
	v_pk_mul_f32 v[152:153], v[182:183], v[152:153] op_sel_hi:[0,1]
	v_cvt_pk_bf16_f32 v147, v152, v153
	v_lshl_add_u64 v[150:151], v[150:151], 0, v[162:163]
	v_cvt_pk_bf16_f32 v148, v148, v149
	v_cvt_pk_bf16_f32 v149, v194, v195
	global_store_dwordx4 v[150:151], v[146:149], off
	v_pk_mul_f32 v[144:145], v[182:183], v[144:145] op_sel_hi:[0,1]
	v_pk_mul_f32 v[142:143], v[182:183], v[142:143] op_sel_hi:[0,1]
	v_pk_mul_f32 v[146:147], v[182:183], v[140:141] op_sel_hi:[0,1]
	v_pk_mul_f32 v[140:141], v[182:183], v[138:139] op_sel_hi:[0,1]
	v_cvt_pk_bf16_f32 v138, v142, v143
	v_cvt_pk_bf16_f32 v139, v144, v145
	v_cvt_pk_bf16_f32 v140, v140, v141
	v_cvt_pk_bf16_f32 v141, v146, v147
	v_or_b32_e32 v146, 16, v180
	v_ashrrev_i32_e32 v147, 31, v146
	global_store_dwordx4 v[150:151], v[138:141], off offset:64
	s_nop 1
	v_lshlrev_b64 v[138:139], 6, v[146:147]
	v_lshl_add_u64 v[152:153], s[24:25], 0, v[138:139]
	global_load_dwordx4 v[138:141], v[152:153], off
	global_load_dwordx4 v[142:145], v[152:153], off offset:16
	global_load_dwordx4 v[148:151], v[152:153], off offset:32
	global_load_dwordx4 v[194:197], v[152:153], off offset:48
	s_waitcnt vmcnt(3)
	v_mov_b32_e32 v152, v139
	v_mov_b32_e32 v153, v140
	v_mov_b32_e32 v139, v141
	s_waitcnt vmcnt(2)
	v_mov_b32_e32 v140, v143
	v_mov_b32_e32 v141, v144
	v_mov_b32_e32 v143, v145
	v_pk_add_f32 v[138:139], v[152:153], v[138:139]
	v_pk_add_f32 v[140:141], v[140:141], v[142:143]
	v_pk_add_f32 v[138:139], v[138:139], v[138:139] op_sel:[0,1] op_sel_hi:[1,0]
	v_pk_add_f32 v[140:141], v[140:141], v[140:141] op_sel:[0,1] op_sel_hi:[1,0]
	s_waitcnt vmcnt(1)
	v_add_f32_e32 v144, v148, v149
	v_add_f32_e32 v148, v150, v151
	s_waitcnt vmcnt(0)
	v_mov_b32_e32 v145, v196
	v_mov_b32_e32 v149, v197
	v_mov_b32_e32 v139, v194
	v_mov_b32_e32 v141, v195
	v_pk_add_f32 v[142:143], v[144:145], v[148:149]
	v_pk_add_f32 v[138:139], v[138:139], v[140:141]
	s_nop 0
	v_pk_add_f32 v[138:139], v[138:139], v[142:143]
	s_nop 0
	v_add_f32_e32 v138, v138, v139
	v_fmamk_f32 v138, v138, 0x3a800000, v186
	v_mul_f32_e32 v139, 0x4f800000, v138
	v_cmp_gt_f32_e32 vcc, s58, v138
	s_nop 1
	v_cndmask_b32_e32 v138, v138, v139, vcc
	v_sqrt_f32_e32 v139, v138
	s_nop 0
	v_add_u32_e32 v140, -1, v139
	v_add_u32_e32 v141, 1, v139
	v_fma_f32 v142, -v140, v139, v138
	v_fma_f32 v143, -v141, v139, v138
	v_cmp_ge_f32_e64 s[14:15], 0, v142
	s_nop 1
	v_cndmask_b32_e64 v139, v139, v140, s[14:15]
	v_cmp_lt_f32_e64 s[14:15], 0, v143
	s_nop 1
	v_cndmask_b32_e64 v139, v139, v141, s[14:15]
	v_mul_f32_e32 v140, 0x37800000, v139
	v_cndmask_b32_e32 v139, v139, v140, vcc
	v_cmp_class_f32_e32 vcc, v138, v187
	s_nop 1
	v_cndmask_b32_e32 v138, v139, v138, vcc
	v_div_scale_f32 v139, s[14:15], v138, v138, 1.0
	v_rcp_f32_e32 v140, v139
	v_div_scale_f32 v141, vcc, 1.0, v138, 1.0
	v_fma_f32 v142, -v139, v140, 1.0
	v_fmac_f32_e32 v140, v142, v140
	v_mul_f32_e32 v142, v141, v140
	v_fma_f32 v143, -v139, v142, v141
	v_fmac_f32_e32 v142, v143, v140
	v_fma_f32 v139, -v139, v142, v141
	v_div_fmas_f32 v139, v139, v140, v142
	v_div_fixup_f32 v148, v139, v138, 1.0
	s_and_b64 vcc, exec, s[10:11]
	v_pk_mul_f32 v[144:145], v[56:57], v[148:149] op_sel_hi:[1,0]
	v_pk_mul_f32 v[142:143], v[54:55], v[148:149] op_sel_hi:[1,0]
	v_pk_mul_f32 v[140:141], v[52:53], v[148:149] op_sel_hi:[1,0]
	v_pk_mul_f32 v[138:139], v[50:51], v[148:149] op_sel_hi:[1,0]
	v_pk_mul_f32 v[136:137], v[136:137], v[148:149] op_sel_hi:[1,0]
	v_pk_mul_f32 v[134:135], v[134:135], v[148:149] op_sel_hi:[1,0]
	v_pk_mul_f32 v[132:133], v[132:133], v[148:149] op_sel_hi:[1,0]
	v_pk_mul_f32 v[130:131], v[130:131], v[148:149] op_sel_hi:[1,0]
	s_cbranch_vccnz .LBB0_696
	v_pk_mul_f32 v[148:149], v[144:145], v[144:145]
	v_pk_mul_f32 v[150:151], v[142:143], v[142:143]
	s_nop 0
	v_pk_mov_b32 v[152:153], v[150:151], v[148:149] op_sel:[1,0]
	v_mov_b32_e32 v151, v149
	v_pk_add_f32 v[148:149], v[152:153], v[150:151]
	v_pk_mul_f32 v[150:151], v[140:141], v[140:141]
	v_pk_add_f32 v[148:149], v[148:149], v[148:149] op_sel_hi:[0,1]
	v_pk_mul_f32 v[152:153], v[138:139], v[138:139]
	v_mul_f32_e32 v148, v134, v134
	v_pk_mov_b32 v[194:195], v[152:153], v[150:151] op_sel:[1,0]
	v_mov_b32_e32 v153, v151
	v_pk_add_f32 v[150:151], v[194:195], v[152:153]
	v_pk_fma_f32 v[152:153], v[134:135], v[134:135], v[148:149] op_sel_hi:[1,1,0]
	v_mul_f32_e32 v148, v136, v136
	v_pk_add_f32 v[150:151], v[150:151], v[150:151] op_sel_hi:[0,1]
	v_pk_fma_f32 v[194:195], v[136:137], v[136:137], v[148:149] op_sel_hi:[1,1,0]
	v_mul_f32_e32 v152, v130, v130
	v_mul_f32_e32 v194, v131, v131
	v_mul_f32_e32 v148, v132, v132
	v_mul_f32_e32 v150, v133, v133
	v_pk_add_f32 v[152:153], v[152:153], v[194:195]
	v_pk_add_f32 v[148:149], v[148:149], v[150:151]
	s_nop 0
	v_pk_add_f32 v[148:149], v[152:153], v[148:149]
	s_nop 0
	v_add_f32_e32 v147, v148, v149
	v_and_b32_e32 v149, 64, v191
	v_xor_b32_e32 v148, 16, v191
	v_add_u32_e32 v149, 64, v149
	v_cmp_lt_i32_e32 vcc, v148, v149
	s_nop 1
	v_cndmask_b32_e32 v148, v191, v148, vcc
	v_lshlrev_b32_e32 v148, 2, v148
	ds_bpermute_b32 v148, v148, v147
	s_waitcnt lgkmcnt(0)
	v_add_f32_e32 v147, v147, v148
	v_xor_b32_e32 v148, 32, v191
	v_cmp_lt_i32_e32 vcc, v148, v149
	s_nop 1
	v_cndmask_b32_e32 v148, v191, v148, vcc
	v_lshlrev_b32_e32 v148, 2, v148
	ds_bpermute_b32 v148, v148, v147
	s_waitcnt lgkmcnt(0)
	v_add_f32_e32 v147, v147, v148
	v_fmamk_f32 v147, v147, 0x3c800000, v186
	v_mul_f32_e32 v148, 0x4f800000, v147
	v_cmp_gt_f32_e32 vcc, s58, v147
	s_nop 1
	v_cndmask_b32_e32 v147, v147, v148, vcc
	v_sqrt_f32_e32 v148, v147
	s_nop 0
	v_add_u32_e32 v149, -1, v148
	v_fma_f32 v150, -v149, v148, v147
	v_cmp_ge_f32_e64 s[14:15], 0, v150
	v_add_u32_e32 v150, 1, v148
	s_nop 0
	v_cndmask_b32_e64 v149, v148, v149, s[14:15]
	v_fma_f32 v148, -v150, v148, v147
	v_cmp_lt_f32_e64 s[14:15], 0, v148
	s_nop 1
	v_cndmask_b32_e64 v148, v149, v150, s[14:15]
	v_mul_f32_e32 v149, 0x37800000, v148
	v_cndmask_b32_e32 v148, v148, v149, vcc
	v_cmp_class_f32_e32 vcc, v147, v187
	s_nop 1
	v_cndmask_b32_e32 v147, v148, v147, vcc
	v_div_scale_f32 v148, s[14:15], v147, v147, 1.0
	v_rcp_f32_e32 v149, v148
	s_nop 0
	v_fma_f32 v150, -v148, v149, 1.0
	v_fmac_f32_e32 v149, v150, v149
	v_div_scale_f32 v150, vcc, 1.0, v147, 1.0
	v_mul_f32_e32 v151, v150, v149
	v_fma_f32 v152, -v148, v151, v150
	v_fmac_f32_e32 v151, v152, v149
	v_fma_f32 v148, -v148, v151, v150
	v_div_fmas_f32 v148, v148, v149, v151
	v_div_fixup_f32 v148, v148, v147, 1.0
	v_pk_mul_f32 v[142:143], v[142:143], v[148:149] op_sel_hi:[1,0]
	v_pk_mul_f32 v[144:145], v[144:145], v[148:149] op_sel_hi:[1,0]
	v_pk_mul_f32 v[138:139], v[138:139], v[148:149] op_sel_hi:[1,0]
	v_pk_mul_f32 v[140:141], v[140:141], v[148:149] op_sel_hi:[1,0]
	v_pk_mul_f32 v[134:135], v[134:135], v[148:149] op_sel_hi:[1,0]
	v_pk_mul_f32 v[136:137], v[136:137], v[148:149] op_sel_hi:[1,0]
	v_pk_mul_f32 v[130:131], v[130:131], v[148:149] op_sel_hi:[1,0]
	v_pk_mul_f32 v[132:133], v[132:133], v[148:149] op_sel_hi:[1,0]
	v_pk_mul_f32 v[144:145], v[88:89], v[144:145]
	v_pk_mul_f32 v[142:143], v[86:87], v[142:143]
	v_pk_mul_f32 v[140:141], v[84:85], v[140:141]
	v_pk_mul_f32 v[138:139], v[82:83], v[138:139]
	v_pk_mul_f32 v[136:137], v[96:97], v[136:137]
	v_pk_mul_f32 v[134:135], v[94:95], v[134:135]
	v_pk_mul_f32 v[132:133], v[92:93], v[132:133]
	v_pk_mul_f32 v[130:131], v[90:91], v[130:131]
	v_cndmask_b32_e64 v147, 0, 1, s[2:3]
	v_cmp_ne_u32_e64 s[14:15], 1, v147
	s_andn2_b64 vcc, exec, s[2:3]
	s_cbranch_vccz .LBB0_697

.LBB0_668:
	v_mov_b32_e32 v183, v182
	v_mov_b32_e32 v148, v182
	v_mov_b32_e32 v149, v182
	v_pk_mul_f32 v[142:143], v[182:183], v[142:143]
	v_pk_mul_f32 v[150:151], v[148:149], v[140:141]
	v_pk_mul_f32 v[140:141], v[182:183], v[138:139]
	v_cvt_pk_bf16_f32 v138, v142, v143
	v_mov_b64_e32 v[142:143], s[22:23]
	v_mad_i64_i32 v[142:143], s[2:3], v146, s60, v[142:143]
	v_lshl_add_u64 v[142:143], s[0:1], 1, v[142:143]
	v_pk_mul_f32 v[144:145], v[148:149], v[144:145]
	v_lshl_add_u64 v[142:143], v[142:143], 0, v[162:163]
	v_cvt_pk_bf16_f32 v139, v144, v145
	v_cvt_pk_bf16_f32 v140, v140, v141
	v_cvt_pk_bf16_f32 v141, v150, v151
	global_store_dwordx4 v[142:143], v[138:141], off
	v_pk_mul_f32 v[136:137], v[148:149], v[136:137]
	v_pk_mul_f32 v[134:135], v[182:183], v[134:135]
	v_pk_mul_f32 v[138:139], v[148:149], v[132:133]
	v_pk_mul_f32 v[132:133], v[182:183], v[130:131]
	v_cvt_pk_bf16_f32 v130, v134, v135
	v_cvt_pk_bf16_f32 v131, v136, v137
	s_nop 0
	v_cvt_pk_bf16_f32 v132, v132, v133
	v_cvt_pk_bf16_f32 v133, v138, v139
	v_or_b32_e32 v138, 32, v180
	v_ashrrev_i32_e32 v139, 31, v138
	global_store_dwordx4 v[142:143], v[130:133], off offset:64
	s_nop 1
	v_lshlrev_b64 v[130:131], 6, v[138:139]
	v_lshl_add_u64 v[144:145], s[24:25], 0, v[130:131]
	global_load_dwordx4 v[130:133], v[144:145], off
	global_load_dwordx4 v[134:137], v[144:145], off offset:16
	global_load_dwordx4 v[140:143], v[144:145], off offset:32
	s_nop 0
	global_load_dwordx4 v[144:147], v[144:145], off offset:48
	s_waitcnt vmcnt(3)
	v_mov_b32_e32 v148, v131
	v_mov_b32_e32 v149, v132
	v_mov_b32_e32 v131, v133
	s_waitcnt vmcnt(2)
	v_mov_b32_e32 v132, v135
	v_mov_b32_e32 v133, v136
	v_mov_b32_e32 v135, v137
	v_pk_add_f32 v[130:131], v[148:149], v[130:131]
	v_pk_add_f32 v[132:133], v[132:133], v[134:135]
	v_pk_add_f32 v[130:131], v[130:131], v[130:131] op_sel:[0,1] op_sel_hi:[1,0]
	v_pk_add_f32 v[132:133], v[132:133], v[132:133] op_sel:[0,1] op_sel_hi:[1,0]
	s_waitcnt vmcnt(1)
	v_add_f32_e32 v136, v140, v141
	v_add_f32_e32 v140, v142, v143
	s_waitcnt vmcnt(0)
	v_mov_b32_e32 v137, v146
	v_mov_b32_e32 v141, v147
	v_mov_b32_e32 v131, v144
	v_mov_b32_e32 v133, v145
	v_pk_add_f32 v[134:135], v[136:137], v[140:141]
	v_pk_add_f32 v[130:131], v[130:131], v[132:133]
	s_nop 0
	v_pk_add_f32 v[130:131], v[130:131], v[134:135]
	s_nop 0
	v_add_f32_e32 v130, v130, v131
	v_fmamk_f32 v130, v130, 0x3a800000, v186
	v_mul_f32_e32 v131, 0x4f800000, v130
	v_cmp_gt_f32_e32 vcc, s58, v130
	s_nop 1
	v_cndmask_b32_e32 v130, v130, v131, vcc
	v_sqrt_f32_e32 v131, v130
	s_nop 0
	v_add_u32_e32 v132, -1, v131
	v_add_u32_e32 v133, 1, v131
	v_fma_f32 v134, -v132, v131, v130
	v_fma_f32 v135, -v133, v131, v130
	v_cmp_ge_f32_e64 s[16:17], 0, v134
	s_nop 1
	v_cndmask_b32_e64 v131, v131, v132, s[16:17]
	v_cmp_lt_f32_e64 s[16:17], 0, v135
	s_nop 1
	v_cndmask_b32_e64 v131, v131, v133, s[16:17]
	v_mul_f32_e32 v132, 0x37800000, v131
	v_cndmask_b32_e32 v131, v131, v132, vcc
	v_cmp_class_f32_e32 vcc, v130, v187
	s_nop 1
	v_cndmask_b32_e32 v130, v131, v130, vcc
	v_div_scale_f32 v131, s[2:3], v130, v130, 1.0
	v_rcp_f32_e32 v132, v131
	v_div_scale_f32 v133, vcc, 1.0, v130, 1.0
	v_fma_f32 v134, -v131, v132, 1.0
	v_fmac_f32_e32 v132, v134, v132
	v_mul_f32_e32 v134, v133, v132
	v_fma_f32 v135, -v131, v134, v133
	v_fmac_f32_e32 v134, v135, v132
	v_fma_f32 v131, -v131, v134, v133
	v_div_fmas_f32 v131, v131, v132, v134
	v_div_fixup_f32 v140, v131, v130, 1.0
	s_and_b64 vcc, exec, s[10:11]
	v_pk_mul_f32 v[136:137], v[48:49], v[140:141] op_sel_hi:[1,0]
	v_pk_mul_f32 v[134:135], v[46:47], v[140:141] op_sel_hi:[1,0]
	v_pk_mul_f32 v[132:133], v[44:45], v[140:141] op_sel_hi:[1,0]
	v_pk_mul_f32 v[130:131], v[42:43], v[140:141] op_sel_hi:[1,0]
	v_pk_mul_f32 v[128:129], v[128:129], v[140:141] op_sel_hi:[1,0]
	v_pk_mul_f32 v[126:127], v[126:127], v[140:141] op_sel_hi:[1,0]
	v_pk_mul_f32 v[124:125], v[124:125], v[140:141] op_sel_hi:[1,0]
	v_pk_mul_f32 v[122:123], v[122:123], v[140:141] op_sel_hi:[1,0]
	s_cbranch_vccnz .LBB0_698
	v_pk_mul_f32 v[140:141], v[136:137], v[136:137]
	v_pk_mul_f32 v[142:143], v[134:135], v[134:135]
	s_nop 0
	v_pk_mov_b32 v[144:145], v[142:143], v[140:141] op_sel:[1,0]
	v_mov_b32_e32 v143, v141
	v_pk_add_f32 v[140:141], v[144:145], v[142:143]
	v_pk_mul_f32 v[142:143], v[132:133], v[132:133]
	v_pk_add_f32 v[140:141], v[140:141], v[140:141] op_sel_hi:[0,1]
	v_pk_mul_f32 v[144:145], v[130:131], v[130:131]
	v_mul_f32_e32 v140, v126, v126
	v_pk_mov_b32 v[146:147], v[144:145], v[142:143] op_sel:[1,0]
	v_mov_b32_e32 v145, v143
	v_pk_add_f32 v[142:143], v[146:147], v[144:145]
	v_pk_fma_f32 v[144:145], v[126:127], v[126:127], v[140:141] op_sel_hi:[1,1,0]
	v_mul_f32_e32 v140, v128, v128
	v_pk_add_f32 v[142:143], v[142:143], v[142:143] op_sel_hi:[0,1]
	v_pk_fma_f32 v[146:147], v[128:129], v[128:129], v[140:141] op_sel_hi:[1,1,0]
	v_mul_f32_e32 v144, v122, v122
	v_mul_f32_e32 v146, v123, v123
	v_mul_f32_e32 v140, v124, v124
	v_mul_f32_e32 v142, v125, v125
	v_pk_add_f32 v[144:145], v[144:145], v[146:147]
	v_pk_add_f32 v[140:141], v[140:141], v[142:143]
	s_nop 0
	v_pk_add_f32 v[140:141], v[144:145], v[140:141]
	s_nop 0
	v_add_f32_e32 v139, v140, v141
	v_and_b32_e32 v141, 64, v191
	v_xor_b32_e32 v140, 16, v191
	v_add_u32_e32 v141, 64, v141
	v_cmp_lt_i32_e32 vcc, v140, v141
	s_nop 1
	v_cndmask_b32_e32 v140, v191, v140, vcc
	v_lshlrev_b32_e32 v140, 2, v140
	ds_bpermute_b32 v140, v140, v139
	s_waitcnt lgkmcnt(0)
	v_add_f32_e32 v139, v139, v140
	v_xor_b32_e32 v140, 32, v191
	v_cmp_lt_i32_e32 vcc, v140, v141
	s_nop 1
	v_cndmask_b32_e32 v140, v191, v140, vcc
	v_lshlrev_b32_e32 v140, 2, v140
	ds_bpermute_b32 v140, v140, v139
	s_waitcnt lgkmcnt(0)
	v_add_f32_e32 v139, v139, v140
	v_fmamk_f32 v139, v139, 0x3c800000, v186
	v_mul_f32_e32 v140, 0x4f800000, v139
	v_cmp_gt_f32_e32 vcc, s58, v139
	s_nop 1
	v_cndmask_b32_e32 v139, v139, v140, vcc
	v_sqrt_f32_e32 v140, v139
	s_nop 0
	v_add_u32_e32 v141, -1, v140
	v_fma_f32 v142, -v141, v140, v139
	v_cmp_ge_f32_e64 s[16:17], 0, v142
	v_add_u32_e32 v142, 1, v140
	s_nop 0
	v_cndmask_b32_e64 v141, v140, v141, s[16:17]
	v_fma_f32 v140, -v142, v140, v139
	v_cmp_lt_f32_e64 s[16:17], 0, v140
	s_nop 1
	v_cndmask_b32_e64 v140, v141, v142, s[16:17]
	v_mul_f32_e32 v141, 0x37800000, v140
	v_cndmask_b32_e32 v140, v140, v141, vcc
	v_cmp_class_f32_e32 vcc, v139, v187
	s_nop 1
	v_cndmask_b32_e32 v139, v140, v139, vcc
	v_div_scale_f32 v140, s[2:3], v139, v139, 1.0
	v_rcp_f32_e32 v141, v140
	s_nop 0
	v_fma_f32 v142, -v140, v141, 1.0
	v_fmac_f32_e32 v141, v142, v141
	v_div_scale_f32 v142, vcc, 1.0, v139, 1.0
	v_mul_f32_e32 v143, v142, v141
	v_fma_f32 v144, -v140, v143, v142
	v_fmac_f32_e32 v143, v144, v141
	v_fma_f32 v140, -v140, v143, v142
	v_div_fmas_f32 v140, v140, v141, v143
	v_div_fixup_f32 v140, v140, v139, 1.0
	v_pk_mul_f32 v[134:135], v[134:135], v[140:141] op_sel_hi:[1,0]
	v_pk_mul_f32 v[136:137], v[136:137], v[140:141] op_sel_hi:[1,0]
	v_pk_mul_f32 v[130:131], v[130:131], v[140:141] op_sel_hi:[1,0]
	v_pk_mul_f32 v[132:133], v[132:133], v[140:141] op_sel_hi:[1,0]
	v_pk_mul_f32 v[126:127], v[126:127], v[140:141] op_sel_hi:[1,0]
	v_pk_mul_f32 v[128:129], v[128:129], v[140:141] op_sel_hi:[1,0]
	v_pk_mul_f32 v[122:123], v[122:123], v[140:141] op_sel_hi:[1,0]
	v_pk_mul_f32 v[124:125], v[124:125], v[140:141] op_sel_hi:[1,0]
	v_pk_mul_f32 v[136:137], v[88:89], v[136:137]
	v_pk_mul_f32 v[134:135], v[86:87], v[134:135]
	v_pk_mul_f32 v[132:133], v[84:85], v[132:133]
	v_pk_mul_f32 v[130:131], v[82:83], v[130:131]
	v_pk_mul_f32 v[128:129], v[96:97], v[128:129]
	v_pk_mul_f32 v[126:127], v[94:95], v[126:127]
	v_pk_mul_f32 v[124:125], v[92:93], v[124:125]
	v_pk_mul_f32 v[122:123], v[90:91], v[122:123]
	s_and_b64 vcc, exec, s[14:15]
	s_cbranch_vccz .LBB0_699

.LBB0_672:
	v_mov_b32_e32 v140, v182
	v_mov_b32_e32 v141, v182
	v_pk_mul_f32 v[134:135], v[182:183], v[134:135]
	v_pk_mul_f32 v[142:143], v[140:141], v[132:133]
	v_pk_mul_f32 v[132:133], v[182:183], v[130:131]
	v_cvt_pk_bf16_f32 v130, v134, v135
	v_mov_b64_e32 v[134:135], s[22:23]
	v_mad_i64_i32 v[134:135], s[2:3], v138, s60, v[134:135]
	v_lshl_add_u64 v[134:135], s[0:1], 1, v[134:135]
	v_pk_mul_f32 v[136:137], v[140:141], v[136:137]
	v_lshl_add_u64 v[134:135], v[134:135], 0, v[162:163]
	v_cvt_pk_bf16_f32 v131, v136, v137
	v_cvt_pk_bf16_f32 v132, v132, v133
	v_cvt_pk_bf16_f32 v133, v142, v143
	global_store_dwordx4 v[134:135], v[130:133], off
	v_pk_mul_f32 v[128:129], v[140:141], v[128:129]
	v_pk_mul_f32 v[126:127], v[182:183], v[126:127]
	v_pk_mul_f32 v[130:131], v[140:141], v[124:125]
	v_pk_mul_f32 v[124:125], v[182:183], v[122:123]
	v_cvt_pk_bf16_f32 v122, v126, v127
	v_cvt_pk_bf16_f32 v123, v128, v129
	s_nop 0
	v_cvt_pk_bf16_f32 v124, v124, v125
	v_cvt_pk_bf16_f32 v125, v130, v131
	v_or_b32_e32 v130, 48, v180
	v_ashrrev_i32_e32 v131, 31, v130
	global_store_dwordx4 v[134:135], v[122:125], off offset:64
	s_nop 1
	v_lshlrev_b64 v[122:123], 6, v[130:131]
	v_lshl_add_u64 v[136:137], s[24:25], 0, v[122:123]
	global_load_dwordx4 v[122:125], v[136:137], off
	global_load_dwordx4 v[126:129], v[136:137], off offset:16
	global_load_dwordx4 v[132:135], v[136:137], off offset:32
	s_nop 0
	global_load_dwordx4 v[136:139], v[136:137], off offset:48
	s_waitcnt vmcnt(3)
	v_mov_b32_e32 v140, v123
	v_mov_b32_e32 v141, v124
	v_mov_b32_e32 v123, v125
	s_waitcnt vmcnt(2)
	v_mov_b32_e32 v124, v127
	v_mov_b32_e32 v125, v128
	v_mov_b32_e32 v127, v129
	v_pk_add_f32 v[122:123], v[140:141], v[122:123]
	v_pk_add_f32 v[124:125], v[124:125], v[126:127]
	v_pk_add_f32 v[122:123], v[122:123], v[122:123] op_sel:[0,1] op_sel_hi:[1,0]
	v_pk_add_f32 v[124:125], v[124:125], v[124:125] op_sel:[0,1] op_sel_hi:[1,0]
	s_waitcnt vmcnt(1)
	v_add_f32_e32 v128, v132, v133
	v_add_f32_e32 v132, v134, v135
	s_waitcnt vmcnt(0)
	v_mov_b32_e32 v129, v138
	v_mov_b32_e32 v133, v139
	v_mov_b32_e32 v123, v136
	v_mov_b32_e32 v125, v137
	v_pk_add_f32 v[126:127], v[128:129], v[132:133]
	v_pk_add_f32 v[122:123], v[122:123], v[124:125]
	s_nop 0
	v_pk_add_f32 v[122:123], v[122:123], v[126:127]
	s_nop 0
	v_add_f32_e32 v122, v122, v123
	v_fmamk_f32 v122, v122, 0x3a800000, v186
	v_mul_f32_e32 v123, 0x4f800000, v122
	v_cmp_gt_f32_e32 vcc, s58, v122
	s_nop 1
	v_cndmask_b32_e32 v122, v122, v123, vcc
	v_sqrt_f32_e32 v123, v122
	s_nop 0
	v_add_u32_e32 v124, -1, v123
	v_add_u32_e32 v125, 1, v123
	v_fma_f32 v126, -v124, v123, v122
	v_fma_f32 v127, -v125, v123, v122
	v_cmp_ge_f32_e64 s[16:17], 0, v126
	s_nop 1
	v_cndmask_b32_e64 v123, v123, v124, s[16:17]
	v_cmp_lt_f32_e64 s[16:17], 0, v127
	s_nop 1
	v_cndmask_b32_e64 v123, v123, v125, s[16:17]
	v_mul_f32_e32 v124, 0x37800000, v123
	v_cndmask_b32_e32 v123, v123, v124, vcc
	v_cmp_class_f32_e32 vcc, v122, v187
	s_nop 1
	v_cndmask_b32_e32 v122, v123, v122, vcc
	v_div_scale_f32 v123, s[2:3], v122, v122, 1.0
	v_rcp_f32_e32 v124, v123
	v_div_scale_f32 v125, vcc, 1.0, v122, 1.0
	v_fma_f32 v126, -v123, v124, 1.0
	v_fmac_f32_e32 v124, v126, v124
	v_mul_f32_e32 v126, v125, v124
	v_fma_f32 v127, -v123, v126, v125
	v_fmac_f32_e32 v126, v127, v124
	v_fma_f32 v123, -v123, v126, v125
	v_div_fmas_f32 v123, v123, v124, v126
	v_div_fixup_f32 v132, v123, v122, 1.0
	s_and_b64 vcc, exec, s[10:11]
	v_pk_mul_f32 v[128:129], v[40:41], v[132:133] op_sel_hi:[1,0]
	v_pk_mul_f32 v[126:127], v[38:39], v[132:133] op_sel_hi:[1,0]
	v_pk_mul_f32 v[124:125], v[36:37], v[132:133] op_sel_hi:[1,0]
	v_pk_mul_f32 v[122:123], v[34:35], v[132:133] op_sel_hi:[1,0]
	v_pk_mul_f32 v[120:121], v[120:121], v[132:133] op_sel_hi:[1,0]
	v_pk_mul_f32 v[118:119], v[118:119], v[132:133] op_sel_hi:[1,0]
	v_pk_mul_f32 v[116:117], v[116:117], v[132:133] op_sel_hi:[1,0]
	v_pk_mul_f32 v[114:115], v[114:115], v[132:133] op_sel_hi:[1,0]
	s_cbranch_vccnz .LBB0_700
	v_pk_mul_f32 v[132:133], v[128:129], v[128:129]
	v_pk_mul_f32 v[134:135], v[126:127], v[126:127]
	s_nop 0
	v_pk_mov_b32 v[136:137], v[134:135], v[132:133] op_sel:[1,0]
	v_mov_b32_e32 v135, v133
	v_pk_add_f32 v[132:133], v[136:137], v[134:135]
	v_pk_mul_f32 v[134:135], v[124:125], v[124:125]
	v_pk_add_f32 v[132:133], v[132:133], v[132:133] op_sel_hi:[0,1]
	v_pk_mul_f32 v[136:137], v[122:123], v[122:123]
	v_mul_f32_e32 v132, v118, v118
	v_pk_mov_b32 v[138:139], v[136:137], v[134:135] op_sel:[1,0]
	v_mov_b32_e32 v137, v135
	v_pk_add_f32 v[134:135], v[138:139], v[136:137]
	v_pk_fma_f32 v[136:137], v[118:119], v[118:119], v[132:133] op_sel_hi:[1,1,0]
	v_mul_f32_e32 v132, v120, v120
	v_pk_add_f32 v[134:135], v[134:135], v[134:135] op_sel_hi:[0,1]
	v_pk_fma_f32 v[138:139], v[120:121], v[120:121], v[132:133] op_sel_hi:[1,1,0]
	v_mul_f32_e32 v136, v114, v114
	v_mul_f32_e32 v138, v115, v115
	v_mul_f32_e32 v132, v116, v116
	v_mul_f32_e32 v134, v117, v117
	v_pk_add_f32 v[136:137], v[136:137], v[138:139]
	v_pk_add_f32 v[132:133], v[132:133], v[134:135]
	s_nop 0
	v_pk_add_f32 v[132:133], v[136:137], v[132:133]
	s_nop 0
	v_add_f32_e32 v131, v132, v133
	v_and_b32_e32 v133, 64, v191
	v_xor_b32_e32 v132, 16, v191
	v_add_u32_e32 v133, 64, v133
	v_cmp_lt_i32_e32 vcc, v132, v133
	s_nop 1
	v_cndmask_b32_e32 v132, v191, v132, vcc
	v_lshlrev_b32_e32 v132, 2, v132
	ds_bpermute_b32 v132, v132, v131
	s_waitcnt lgkmcnt(0)
	v_add_f32_e32 v131, v131, v132
	v_xor_b32_e32 v132, 32, v191
	v_cmp_lt_i32_e32 vcc, v132, v133
	s_nop 1
	v_cndmask_b32_e32 v132, v191, v132, vcc
	v_lshlrev_b32_e32 v132, 2, v132
	ds_bpermute_b32 v132, v132, v131
	s_waitcnt lgkmcnt(0)
	v_add_f32_e32 v131, v131, v132
	v_fmamk_f32 v131, v131, 0x3c800000, v186
	v_mul_f32_e32 v132, 0x4f800000, v131
	v_cmp_gt_f32_e32 vcc, s58, v131
	s_nop 1
	v_cndmask_b32_e32 v131, v131, v132, vcc
	v_sqrt_f32_e32 v132, v131
	s_nop 0
	v_add_u32_e32 v133, -1, v132
	v_fma_f32 v134, -v133, v132, v131
	v_cmp_ge_f32_e64 s[16:17], 0, v134
	v_add_u32_e32 v134, 1, v132
	s_nop 0
	v_cndmask_b32_e64 v133, v132, v133, s[16:17]
	v_fma_f32 v132, -v134, v132, v131
	v_cmp_lt_f32_e64 s[16:17], 0, v132
	s_nop 1
	v_cndmask_b32_e64 v132, v133, v134, s[16:17]
	v_mul_f32_e32 v133, 0x37800000, v132
	v_cndmask_b32_e32 v132, v132, v133, vcc
	v_cmp_class_f32_e32 vcc, v131, v187
	s_nop 1
	v_cndmask_b32_e32 v131, v132, v131, vcc
	v_div_scale_f32 v132, s[2:3], v131, v131, 1.0
	v_rcp_f32_e32 v133, v132
	s_nop 0
	v_fma_f32 v134, -v132, v133, 1.0
	v_fmac_f32_e32 v133, v134, v133
	v_div_scale_f32 v134, vcc, 1.0, v131, 1.0
	v_mul_f32_e32 v135, v134, v133
	v_fma_f32 v136, -v132, v135, v134
	v_fmac_f32_e32 v135, v136, v133
	v_fma_f32 v132, -v132, v135, v134
	v_div_fmas_f32 v132, v132, v133, v135
	v_div_fixup_f32 v132, v132, v131, 1.0
	v_pk_mul_f32 v[126:127], v[126:127], v[132:133] op_sel_hi:[1,0]
	v_pk_mul_f32 v[128:129], v[128:129], v[132:133] op_sel_hi:[1,0]
	v_pk_mul_f32 v[122:123], v[122:123], v[132:133] op_sel_hi:[1,0]
	v_pk_mul_f32 v[124:125], v[124:125], v[132:133] op_sel_hi:[1,0]
	v_pk_mul_f32 v[118:119], v[118:119], v[132:133] op_sel_hi:[1,0]
	v_pk_mul_f32 v[120:121], v[120:121], v[132:133] op_sel_hi:[1,0]
	v_pk_mul_f32 v[114:115], v[114:115], v[132:133] op_sel_hi:[1,0]
	v_pk_mul_f32 v[116:117], v[116:117], v[132:133] op_sel_hi:[1,0]
	v_pk_mul_f32 v[128:129], v[88:89], v[128:129]
	v_pk_mul_f32 v[126:127], v[86:87], v[126:127]
	v_pk_mul_f32 v[124:125], v[84:85], v[124:125]
	v_pk_mul_f32 v[122:123], v[82:83], v[122:123]
	v_pk_mul_f32 v[120:121], v[96:97], v[120:121]
	v_pk_mul_f32 v[118:119], v[94:95], v[118:119]
	v_pk_mul_f32 v[116:117], v[92:93], v[116:117]
	v_pk_mul_f32 v[114:115], v[90:91], v[114:115]
	s_and_b64 vcc, exec, s[14:15]
	s_cbranch_vccz .LBB0_701

.LBB0_676:
	v_mov_b32_e32 v132, v182
	v_mov_b32_e32 v133, v182
	v_pk_mul_f32 v[126:127], v[182:183], v[126:127]
	v_pk_mul_f32 v[134:135], v[132:133], v[124:125]
	v_pk_mul_f32 v[124:125], v[182:183], v[122:123]
	v_cvt_pk_bf16_f32 v122, v126, v127
	v_mov_b64_e32 v[126:127], s[22:23]
	v_mad_i64_i32 v[126:127], s[2:3], v130, s60, v[126:127]
	v_lshl_add_u64 v[126:127], s[0:1], 1, v[126:127]
	v_pk_mul_f32 v[128:129], v[132:133], v[128:129]
	v_lshl_add_u64 v[126:127], v[126:127], 0, v[162:163]
	v_cvt_pk_bf16_f32 v123, v128, v129
	v_cvt_pk_bf16_f32 v124, v124, v125
	v_cvt_pk_bf16_f32 v125, v134, v135
	global_store_dwordx4 v[126:127], v[122:125], off
	v_pk_mul_f32 v[120:121], v[132:133], v[120:121]
	v_pk_mul_f32 v[118:119], v[182:183], v[118:119]
	v_pk_mul_f32 v[122:123], v[132:133], v[116:117]
	v_pk_mul_f32 v[116:117], v[182:183], v[114:115]
	v_cvt_pk_bf16_f32 v114, v118, v119
	v_cvt_pk_bf16_f32 v115, v120, v121
	s_nop 0
	v_cvt_pk_bf16_f32 v116, v116, v117
	v_cvt_pk_bf16_f32 v117, v122, v123
	v_add_u32_e32 v122, 0x80, v180
	v_ashrrev_i32_e32 v123, 31, v122
	global_store_dwordx4 v[126:127], v[114:117], off offset:64
	s_nop 1
	v_lshlrev_b64 v[114:115], 6, v[122:123]
	v_lshl_add_u64 v[128:129], s[24:25], 0, v[114:115]
	global_load_dwordx4 v[114:117], v[128:129], off
	global_load_dwordx4 v[118:121], v[128:129], off offset:16
	global_load_dwordx4 v[124:127], v[128:129], off offset:32
	s_nop 0
	global_load_dwordx4 v[128:131], v[128:129], off offset:48
	s_waitcnt vmcnt(3)
	v_mov_b32_e32 v132, v115
	v_mov_b32_e32 v133, v116
	v_mov_b32_e32 v115, v117
	s_waitcnt vmcnt(2)
	v_mov_b32_e32 v116, v119
	v_mov_b32_e32 v117, v120
	v_mov_b32_e32 v119, v121
	v_pk_add_f32 v[114:115], v[132:133], v[114:115]
	v_pk_add_f32 v[116:117], v[116:117], v[118:119]
	v_pk_add_f32 v[114:115], v[114:115], v[114:115] op_sel:[0,1] op_sel_hi:[1,0]
	v_pk_add_f32 v[116:117], v[116:117], v[116:117] op_sel:[0,1] op_sel_hi:[1,0]
	s_waitcnt vmcnt(1)
	v_add_f32_e32 v120, v124, v125
	v_add_f32_e32 v124, v126, v127
	s_waitcnt vmcnt(0)
	v_mov_b32_e32 v121, v130
	v_mov_b32_e32 v125, v131
	v_mov_b32_e32 v115, v128
	v_mov_b32_e32 v117, v129
	v_pk_add_f32 v[118:119], v[120:121], v[124:125]
	v_pk_add_f32 v[114:115], v[114:115], v[116:117]
	s_nop 0
	v_pk_add_f32 v[114:115], v[114:115], v[118:119]
	s_nop 0
	v_add_f32_e32 v114, v114, v115
	v_fmamk_f32 v114, v114, 0x3a800000, v186
	v_mul_f32_e32 v115, 0x4f800000, v114
	v_cmp_gt_f32_e32 vcc, s58, v114
	s_nop 1
	v_cndmask_b32_e32 v114, v114, v115, vcc
	v_sqrt_f32_e32 v115, v114
	s_nop 0
	v_add_u32_e32 v116, -1, v115
	v_add_u32_e32 v117, 1, v115
	v_fma_f32 v118, -v116, v115, v114
	v_fma_f32 v119, -v117, v115, v114
	v_cmp_ge_f32_e64 s[16:17], 0, v118
	s_nop 1
	v_cndmask_b32_e64 v115, v115, v116, s[16:17]
	v_cmp_lt_f32_e64 s[16:17], 0, v119
	s_nop 1
	v_cndmask_b32_e64 v115, v115, v117, s[16:17]
	v_mul_f32_e32 v116, 0x37800000, v115
	v_cndmask_b32_e32 v115, v115, v116, vcc
	v_cmp_class_f32_e32 vcc, v114, v187
	s_nop 1
	v_cndmask_b32_e32 v114, v115, v114, vcc
	v_div_scale_f32 v115, s[2:3], v114, v114, 1.0
	v_rcp_f32_e32 v116, v115
	v_div_scale_f32 v117, vcc, 1.0, v114, 1.0
	v_fma_f32 v118, -v115, v116, 1.0
	v_fmac_f32_e32 v116, v118, v116
	v_mul_f32_e32 v118, v117, v116
	v_fma_f32 v119, -v115, v118, v117
	v_fmac_f32_e32 v118, v119, v116
	v_fma_f32 v115, -v115, v118, v117
	v_div_fmas_f32 v115, v115, v116, v118
	v_div_fixup_f32 v124, v115, v114, 1.0
	s_and_b64 vcc, exec, s[10:11]
	v_pk_mul_f32 v[120:121], v[32:33], v[124:125] op_sel_hi:[1,0]
	v_pk_mul_f32 v[118:119], v[30:31], v[124:125] op_sel_hi:[1,0]
	v_pk_mul_f32 v[116:117], v[28:29], v[124:125] op_sel_hi:[1,0]
	v_pk_mul_f32 v[114:115], v[26:27], v[124:125] op_sel_hi:[1,0]
	v_pk_mul_f32 v[112:113], v[112:113], v[124:125] op_sel_hi:[1,0]
	v_pk_mul_f32 v[110:111], v[110:111], v[124:125] op_sel_hi:[1,0]
	v_pk_mul_f32 v[108:109], v[108:109], v[124:125] op_sel_hi:[1,0]
	v_pk_mul_f32 v[106:107], v[106:107], v[124:125] op_sel_hi:[1,0]
	s_cbranch_vccnz .LBB0_702
	v_pk_mul_f32 v[124:125], v[120:121], v[120:121]
	v_pk_mul_f32 v[126:127], v[118:119], v[118:119]
	s_nop 0
	v_pk_mov_b32 v[128:129], v[126:127], v[124:125] op_sel:[1,0]
	v_mov_b32_e32 v127, v125
	v_pk_add_f32 v[124:125], v[128:129], v[126:127]
	v_pk_mul_f32 v[126:127], v[116:117], v[116:117]
	v_pk_add_f32 v[124:125], v[124:125], v[124:125] op_sel_hi:[0,1]
	v_pk_mul_f32 v[128:129], v[114:115], v[114:115]
	v_mul_f32_e32 v124, v110, v110
	v_pk_mov_b32 v[130:131], v[128:129], v[126:127] op_sel:[1,0]
	v_mov_b32_e32 v129, v127
	v_pk_add_f32 v[126:127], v[130:131], v[128:129]
	v_pk_fma_f32 v[128:129], v[110:111], v[110:111], v[124:125] op_sel_hi:[1,1,0]
	v_mul_f32_e32 v124, v112, v112
	v_pk_add_f32 v[126:127], v[126:127], v[126:127] op_sel_hi:[0,1]
	v_pk_fma_f32 v[130:131], v[112:113], v[112:113], v[124:125] op_sel_hi:[1,1,0]
	v_mul_f32_e32 v128, v106, v106
	v_mul_f32_e32 v130, v107, v107
	v_mul_f32_e32 v124, v108, v108
	v_mul_f32_e32 v126, v109, v109
	v_pk_add_f32 v[128:129], v[128:129], v[130:131]
	v_pk_add_f32 v[124:125], v[124:125], v[126:127]
	s_nop 0
	v_pk_add_f32 v[124:125], v[128:129], v[124:125]
	s_nop 0
	v_add_f32_e32 v123, v124, v125
	v_and_b32_e32 v125, 64, v191
	v_xor_b32_e32 v124, 16, v191
	v_add_u32_e32 v125, 64, v125
	v_cmp_lt_i32_e32 vcc, v124, v125
	s_nop 1
	v_cndmask_b32_e32 v124, v191, v124, vcc
	v_lshlrev_b32_e32 v124, 2, v124
	ds_bpermute_b32 v124, v124, v123
	s_waitcnt lgkmcnt(0)
	v_add_f32_e32 v123, v123, v124
	v_xor_b32_e32 v124, 32, v191
	v_cmp_lt_i32_e32 vcc, v124, v125
	s_nop 1
	v_cndmask_b32_e32 v124, v191, v124, vcc
	v_lshlrev_b32_e32 v124, 2, v124
	ds_bpermute_b32 v124, v124, v123
	s_waitcnt lgkmcnt(0)
	v_add_f32_e32 v123, v123, v124
	v_fmamk_f32 v123, v123, 0x3c800000, v186
	v_mul_f32_e32 v124, 0x4f800000, v123
	v_cmp_gt_f32_e32 vcc, s58, v123
	s_nop 1
	v_cndmask_b32_e32 v123, v123, v124, vcc
	v_sqrt_f32_e32 v124, v123
	s_nop 0
	v_add_u32_e32 v125, -1, v124
	v_fma_f32 v126, -v125, v124, v123
	v_cmp_ge_f32_e64 s[16:17], 0, v126
	v_add_u32_e32 v126, 1, v124
	s_nop 0
	v_cndmask_b32_e64 v125, v124, v125, s[16:17]
	v_fma_f32 v124, -v126, v124, v123
	v_cmp_lt_f32_e64 s[16:17], 0, v124
	s_nop 1
	v_cndmask_b32_e64 v124, v125, v126, s[16:17]
	v_mul_f32_e32 v125, 0x37800000, v124
	v_cndmask_b32_e32 v124, v124, v125, vcc
	v_cmp_class_f32_e32 vcc, v123, v187
	s_nop 1
	v_cndmask_b32_e32 v123, v124, v123, vcc
	v_div_scale_f32 v124, s[2:3], v123, v123, 1.0
	v_rcp_f32_e32 v125, v124
	s_nop 0
	v_fma_f32 v126, -v124, v125, 1.0
	v_fmac_f32_e32 v125, v126, v125
	v_div_scale_f32 v126, vcc, 1.0, v123, 1.0
	v_mul_f32_e32 v127, v126, v125
	v_fma_f32 v128, -v124, v127, v126
	v_fmac_f32_e32 v127, v128, v125
	v_fma_f32 v124, -v124, v127, v126
	v_div_fmas_f32 v124, v124, v125, v127
	v_div_fixup_f32 v124, v124, v123, 1.0
	v_pk_mul_f32 v[118:119], v[118:119], v[124:125] op_sel_hi:[1,0]
	v_pk_mul_f32 v[120:121], v[120:121], v[124:125] op_sel_hi:[1,0]
	v_pk_mul_f32 v[114:115], v[114:115], v[124:125] op_sel_hi:[1,0]
	v_pk_mul_f32 v[116:117], v[116:117], v[124:125] op_sel_hi:[1,0]
	v_pk_mul_f32 v[110:111], v[110:111], v[124:125] op_sel_hi:[1,0]
	v_pk_mul_f32 v[112:113], v[112:113], v[124:125] op_sel_hi:[1,0]
	v_pk_mul_f32 v[106:107], v[106:107], v[124:125] op_sel_hi:[1,0]
	v_pk_mul_f32 v[108:109], v[108:109], v[124:125] op_sel_hi:[1,0]
	v_pk_mul_f32 v[120:121], v[88:89], v[120:121]
	v_pk_mul_f32 v[118:119], v[86:87], v[118:119]
	v_pk_mul_f32 v[116:117], v[84:85], v[116:117]
	v_pk_mul_f32 v[114:115], v[82:83], v[114:115]
	v_pk_mul_f32 v[112:113], v[96:97], v[112:113]
	v_pk_mul_f32 v[110:111], v[94:95], v[110:111]
	v_pk_mul_f32 v[108:109], v[92:93], v[108:109]
	v_pk_mul_f32 v[106:107], v[90:91], v[106:107]
	s_and_b64 vcc, exec, s[14:15]
	s_cbranch_vccz .LBB0_703

.LBB0_680:
	v_mov_b32_e32 v124, v182
	v_mov_b32_e32 v125, v182
	v_pk_mul_f32 v[118:119], v[182:183], v[118:119]
	v_pk_mul_f32 v[126:127], v[124:125], v[116:117]
	v_pk_mul_f32 v[116:117], v[182:183], v[114:115]
	v_cvt_pk_bf16_f32 v114, v118, v119
	v_mov_b64_e32 v[118:119], s[22:23]
	v_mad_i64_i32 v[118:119], s[2:3], v122, s60, v[118:119]
	v_lshl_add_u64 v[118:119], s[0:1], 1, v[118:119]
	v_pk_mul_f32 v[120:121], v[124:125], v[120:121]
	v_lshl_add_u64 v[118:119], v[118:119], 0, v[162:163]
	v_cvt_pk_bf16_f32 v115, v120, v121
	v_cvt_pk_bf16_f32 v116, v116, v117
	v_cvt_pk_bf16_f32 v117, v126, v127
	global_store_dwordx4 v[118:119], v[114:117], off
	v_pk_mul_f32 v[112:113], v[124:125], v[112:113]
	v_pk_mul_f32 v[110:111], v[182:183], v[110:111]
	v_pk_mul_f32 v[114:115], v[124:125], v[108:109]
	v_pk_mul_f32 v[108:109], v[182:183], v[106:107]
	v_cvt_pk_bf16_f32 v106, v110, v111
	v_cvt_pk_bf16_f32 v107, v112, v113
	s_nop 0
	v_cvt_pk_bf16_f32 v108, v108, v109
	v_cvt_pk_bf16_f32 v109, v114, v115
	v_add_u32_e32 v114, 0x90, v180
	v_ashrrev_i32_e32 v115, 31, v114
	global_store_dwordx4 v[118:119], v[106:109], off offset:64
	s_nop 1
	v_lshlrev_b64 v[106:107], 6, v[114:115]
	v_lshl_add_u64 v[120:121], s[24:25], 0, v[106:107]
	global_load_dwordx4 v[106:109], v[120:121], off
	global_load_dwordx4 v[110:113], v[120:121], off offset:16
	global_load_dwordx4 v[116:119], v[120:121], off offset:32
	s_nop 0
	global_load_dwordx4 v[120:123], v[120:121], off offset:48
	s_waitcnt vmcnt(3)
	v_mov_b32_e32 v124, v107
	v_mov_b32_e32 v125, v108
	v_mov_b32_e32 v107, v109
	s_waitcnt vmcnt(2)
	v_mov_b32_e32 v108, v111
	v_mov_b32_e32 v109, v112
	v_mov_b32_e32 v111, v113
	v_pk_add_f32 v[106:107], v[124:125], v[106:107]
	v_pk_add_f32 v[108:109], v[108:109], v[110:111]
	v_pk_add_f32 v[106:107], v[106:107], v[106:107] op_sel:[0,1] op_sel_hi:[1,0]
	v_pk_add_f32 v[108:109], v[108:109], v[108:109] op_sel:[0,1] op_sel_hi:[1,0]
	s_waitcnt vmcnt(1)
	v_add_f32_e32 v112, v116, v117
	v_add_f32_e32 v116, v118, v119
	s_waitcnt vmcnt(0)
	v_mov_b32_e32 v113, v122
	v_mov_b32_e32 v117, v123
	v_mov_b32_e32 v107, v120
	v_mov_b32_e32 v109, v121
	v_pk_add_f32 v[110:111], v[112:113], v[116:117]
	v_pk_add_f32 v[106:107], v[106:107], v[108:109]
	s_nop 0
	v_pk_add_f32 v[106:107], v[106:107], v[110:111]
	s_nop 0
	v_add_f32_e32 v106, v106, v107
	v_fmamk_f32 v106, v106, 0x3a800000, v186
	v_mul_f32_e32 v107, 0x4f800000, v106
	v_cmp_gt_f32_e32 vcc, s58, v106
	s_nop 1
	v_cndmask_b32_e32 v106, v106, v107, vcc
	v_sqrt_f32_e32 v107, v106
	s_nop 0
	v_add_u32_e32 v108, -1, v107
	v_add_u32_e32 v109, 1, v107
	v_fma_f32 v110, -v108, v107, v106
	v_fma_f32 v111, -v109, v107, v106
	v_cmp_ge_f32_e64 s[16:17], 0, v110
	s_nop 1
	v_cndmask_b32_e64 v107, v107, v108, s[16:17]
	v_cmp_lt_f32_e64 s[16:17], 0, v111
	s_nop 1
	v_cndmask_b32_e64 v107, v107, v109, s[16:17]
	v_mul_f32_e32 v108, 0x37800000, v107
	v_cndmask_b32_e32 v107, v107, v108, vcc
	v_cmp_class_f32_e32 vcc, v106, v187
	s_nop 1
	v_cndmask_b32_e32 v106, v107, v106, vcc
	v_div_scale_f32 v107, s[2:3], v106, v106, 1.0
	v_rcp_f32_e32 v108, v107
	v_div_scale_f32 v109, vcc, 1.0, v106, 1.0
	v_fma_f32 v110, -v107, v108, 1.0
	v_fmac_f32_e32 v108, v110, v108
	v_mul_f32_e32 v110, v109, v108
	v_fma_f32 v111, -v107, v110, v109
	v_fmac_f32_e32 v110, v111, v108
	v_fma_f32 v107, -v107, v110, v109
	v_div_fmas_f32 v107, v107, v108, v110
	v_div_fixup_f32 v116, v107, v106, 1.0
	s_and_b64 vcc, exec, s[10:11]
	v_pk_mul_f32 v[112:113], v[24:25], v[116:117] op_sel_hi:[1,0]
	v_pk_mul_f32 v[110:111], v[22:23], v[116:117] op_sel_hi:[1,0]
	v_pk_mul_f32 v[108:109], v[20:21], v[116:117] op_sel_hi:[1,0]
	v_pk_mul_f32 v[106:107], v[18:19], v[116:117] op_sel_hi:[1,0]
	v_pk_mul_f32 v[104:105], v[104:105], v[116:117] op_sel_hi:[1,0]
	v_pk_mul_f32 v[102:103], v[102:103], v[116:117] op_sel_hi:[1,0]
	v_pk_mul_f32 v[100:101], v[100:101], v[116:117] op_sel_hi:[1,0]
	v_pk_mul_f32 v[98:99], v[98:99], v[116:117] op_sel_hi:[1,0]
	s_cbranch_vccnz .LBB0_704
	v_pk_mul_f32 v[116:117], v[112:113], v[112:113]
	v_pk_mul_f32 v[118:119], v[110:111], v[110:111]
	s_nop 0
	v_pk_mov_b32 v[120:121], v[118:119], v[116:117] op_sel:[1,0]
	v_mov_b32_e32 v119, v117
	v_pk_add_f32 v[116:117], v[120:121], v[118:119]
	v_pk_mul_f32 v[118:119], v[108:109], v[108:109]
	v_pk_add_f32 v[116:117], v[116:117], v[116:117] op_sel_hi:[0,1]
	v_pk_mul_f32 v[120:121], v[106:107], v[106:107]
	v_mul_f32_e32 v116, v102, v102
	v_pk_mov_b32 v[122:123], v[120:121], v[118:119] op_sel:[1,0]
	v_mov_b32_e32 v121, v119
	v_pk_add_f32 v[118:119], v[122:123], v[120:121]
	v_pk_fma_f32 v[120:121], v[102:103], v[102:103], v[116:117] op_sel_hi:[1,1,0]
	v_mul_f32_e32 v116, v104, v104
	v_pk_add_f32 v[118:119], v[118:119], v[118:119] op_sel_hi:[0,1]
	v_pk_fma_f32 v[122:123], v[104:105], v[104:105], v[116:117] op_sel_hi:[1,1,0]
	v_mul_f32_e32 v120, v98, v98
	v_mul_f32_e32 v122, v99, v99
	v_mul_f32_e32 v116, v100, v100
	v_mul_f32_e32 v118, v101, v101
	v_pk_add_f32 v[120:121], v[120:121], v[122:123]
	v_pk_add_f32 v[116:117], v[116:117], v[118:119]
	s_nop 0
	v_pk_add_f32 v[116:117], v[120:121], v[116:117]
	s_nop 0
	v_add_f32_e32 v115, v116, v117
	v_and_b32_e32 v117, 64, v191
	v_xor_b32_e32 v116, 16, v191
	v_add_u32_e32 v117, 64, v117
	v_cmp_lt_i32_e32 vcc, v116, v117
	s_nop 1
	v_cndmask_b32_e32 v116, v191, v116, vcc
	v_lshlrev_b32_e32 v116, 2, v116
	ds_bpermute_b32 v116, v116, v115
	s_waitcnt lgkmcnt(0)
	v_add_f32_e32 v115, v115, v116
	v_xor_b32_e32 v116, 32, v191
	v_cmp_lt_i32_e32 vcc, v116, v117
	s_nop 1
	v_cndmask_b32_e32 v116, v191, v116, vcc
	v_lshlrev_b32_e32 v116, 2, v116
	ds_bpermute_b32 v116, v116, v115
	s_waitcnt lgkmcnt(0)
	v_add_f32_e32 v115, v115, v116
	v_fmamk_f32 v115, v115, 0x3c800000, v186
	v_mul_f32_e32 v116, 0x4f800000, v115
	v_cmp_gt_f32_e32 vcc, s58, v115
	s_nop 1
	v_cndmask_b32_e32 v115, v115, v116, vcc
	v_sqrt_f32_e32 v116, v115
	s_nop 0
	v_add_u32_e32 v117, -1, v116
	v_fma_f32 v118, -v117, v116, v115
	v_cmp_ge_f32_e64 s[16:17], 0, v118
	v_add_u32_e32 v118, 1, v116
	s_nop 0
	v_cndmask_b32_e64 v117, v116, v117, s[16:17]
	v_fma_f32 v116, -v118, v116, v115
	v_cmp_lt_f32_e64 s[16:17], 0, v116
	s_nop 1
	v_cndmask_b32_e64 v116, v117, v118, s[16:17]
	v_mul_f32_e32 v117, 0x37800000, v116
	v_cndmask_b32_e32 v116, v116, v117, vcc
	v_cmp_class_f32_e32 vcc, v115, v187
	s_nop 1
	v_cndmask_b32_e32 v115, v116, v115, vcc
	v_div_scale_f32 v116, s[2:3], v115, v115, 1.0
	v_rcp_f32_e32 v117, v116
	s_nop 0
	v_fma_f32 v118, -v116, v117, 1.0
	v_fmac_f32_e32 v117, v118, v117
	v_div_scale_f32 v118, vcc, 1.0, v115, 1.0
	v_mul_f32_e32 v119, v118, v117
	v_fma_f32 v120, -v116, v119, v118
	v_fmac_f32_e32 v119, v120, v117
	v_fma_f32 v116, -v116, v119, v118
	v_div_fmas_f32 v116, v116, v117, v119
	v_div_fixup_f32 v116, v116, v115, 1.0
	v_pk_mul_f32 v[110:111], v[110:111], v[116:117] op_sel_hi:[1,0]
	v_pk_mul_f32 v[112:113], v[112:113], v[116:117] op_sel_hi:[1,0]
	v_pk_mul_f32 v[106:107], v[106:107], v[116:117] op_sel_hi:[1,0]
	v_pk_mul_f32 v[108:109], v[108:109], v[116:117] op_sel_hi:[1,0]
	v_pk_mul_f32 v[102:103], v[102:103], v[116:117] op_sel_hi:[1,0]
	v_pk_mul_f32 v[104:105], v[104:105], v[116:117] op_sel_hi:[1,0]
	v_pk_mul_f32 v[98:99], v[98:99], v[116:117] op_sel_hi:[1,0]
	v_pk_mul_f32 v[100:101], v[100:101], v[116:117] op_sel_hi:[1,0]
	v_pk_mul_f32 v[112:113], v[88:89], v[112:113]
	v_pk_mul_f32 v[110:111], v[86:87], v[110:111]
	v_pk_mul_f32 v[108:109], v[84:85], v[108:109]
	v_pk_mul_f32 v[106:107], v[82:83], v[106:107]
	v_pk_mul_f32 v[104:105], v[96:97], v[104:105]
	v_pk_mul_f32 v[102:103], v[94:95], v[102:103]
	v_pk_mul_f32 v[100:101], v[92:93], v[100:101]
	v_pk_mul_f32 v[98:99], v[90:91], v[98:99]
	s_and_b64 vcc, exec, s[14:15]
	s_cbranch_vccz .LBB0_705

.LBB0_684:
	v_mov_b32_e32 v116, v182
	v_mov_b32_e32 v117, v182
	v_pk_mul_f32 v[110:111], v[182:183], v[110:111]
	v_pk_mul_f32 v[118:119], v[116:117], v[108:109]
	v_pk_mul_f32 v[108:109], v[182:183], v[106:107]
	v_cvt_pk_bf16_f32 v106, v110, v111
	v_mov_b64_e32 v[110:111], s[22:23]
	v_mad_i64_i32 v[110:111], s[2:3], v114, s60, v[110:111]
	v_lshl_add_u64 v[110:111], s[0:1], 1, v[110:111]
	v_pk_mul_f32 v[112:113], v[116:117], v[112:113]
	v_lshl_add_u64 v[110:111], v[110:111], 0, v[162:163]
	v_cvt_pk_bf16_f32 v107, v112, v113
	v_cvt_pk_bf16_f32 v108, v108, v109
	v_cvt_pk_bf16_f32 v109, v118, v119
	global_store_dwordx4 v[110:111], v[106:109], off
	v_pk_mul_f32 v[104:105], v[116:117], v[104:105]
	v_pk_mul_f32 v[102:103], v[182:183], v[102:103]
	v_pk_mul_f32 v[106:107], v[116:117], v[100:101]
	v_pk_mul_f32 v[100:101], v[182:183], v[98:99]
	v_cvt_pk_bf16_f32 v98, v102, v103
	v_cvt_pk_bf16_f32 v99, v104, v105
	s_nop 0
	v_cvt_pk_bf16_f32 v100, v100, v101
	v_cvt_pk_bf16_f32 v101, v106, v107
	v_add_u32_e32 v106, 0xa0, v180
	v_ashrrev_i32_e32 v107, 31, v106
	global_store_dwordx4 v[110:111], v[98:101], off offset:64
	s_nop 1
	v_lshlrev_b64 v[98:99], 6, v[106:107]
	v_lshl_add_u64 v[112:113], s[24:25], 0, v[98:99]
	global_load_dwordx4 v[98:101], v[112:113], off
	global_load_dwordx4 v[102:105], v[112:113], off offset:16
	global_load_dwordx4 v[108:111], v[112:113], off offset:32
	s_nop 0
	global_load_dwordx4 v[112:115], v[112:113], off offset:48
	s_waitcnt vmcnt(3)
	v_mov_b32_e32 v116, v99
	v_mov_b32_e32 v117, v100
	v_mov_b32_e32 v99, v101
	s_waitcnt vmcnt(2)
	v_mov_b32_e32 v100, v103
	v_mov_b32_e32 v101, v104
	v_mov_b32_e32 v103, v105
	v_pk_add_f32 v[98:99], v[116:117], v[98:99]
	v_pk_add_f32 v[100:101], v[100:101], v[102:103]
	v_pk_add_f32 v[98:99], v[98:99], v[98:99] op_sel:[0,1] op_sel_hi:[1,0]
	v_pk_add_f32 v[100:101], v[100:101], v[100:101] op_sel:[0,1] op_sel_hi:[1,0]
	s_waitcnt vmcnt(1)
	v_add_f32_e32 v104, v108, v109
	v_add_f32_e32 v108, v110, v111
	s_waitcnt vmcnt(0)
	v_mov_b32_e32 v105, v114
	v_mov_b32_e32 v109, v115
	v_mov_b32_e32 v99, v112
	v_mov_b32_e32 v101, v113
	v_pk_add_f32 v[102:103], v[104:105], v[108:109]
	v_pk_add_f32 v[98:99], v[98:99], v[100:101]
	s_nop 0
	v_pk_add_f32 v[98:99], v[98:99], v[102:103]
	s_nop 0
	v_add_f32_e32 v98, v98, v99
	v_fmamk_f32 v98, v98, 0x3a800000, v186
	v_mul_f32_e32 v99, 0x4f800000, v98
	v_cmp_gt_f32_e32 vcc, s58, v98
	s_nop 1
	v_cndmask_b32_e32 v98, v98, v99, vcc
	v_sqrt_f32_e32 v99, v98
	s_nop 0
	v_add_u32_e32 v100, -1, v99
	v_add_u32_e32 v101, 1, v99
	v_fma_f32 v102, -v100, v99, v98
	v_fma_f32 v103, -v101, v99, v98
	v_cmp_ge_f32_e64 s[16:17], 0, v102
	s_nop 1
	v_cndmask_b32_e64 v99, v99, v100, s[16:17]
	v_cmp_lt_f32_e64 s[16:17], 0, v103
	s_nop 1
	v_cndmask_b32_e64 v99, v99, v101, s[16:17]
	v_mul_f32_e32 v100, 0x37800000, v99
	v_cndmask_b32_e32 v99, v99, v100, vcc
	v_cmp_class_f32_e32 vcc, v98, v187
	s_nop 1
	v_cndmask_b32_e32 v98, v99, v98, vcc
	v_div_scale_f32 v99, s[2:3], v98, v98, 1.0
	v_rcp_f32_e32 v100, v99
	v_div_scale_f32 v101, vcc, 1.0, v98, 1.0
	v_fma_f32 v102, -v99, v100, 1.0
	v_fmac_f32_e32 v100, v102, v100
	v_mul_f32_e32 v102, v101, v100
	v_fma_f32 v103, -v99, v102, v101
	v_fmac_f32_e32 v102, v103, v100
	v_fma_f32 v99, -v99, v102, v101
	v_div_fmas_f32 v99, v99, v100, v102
	v_div_fixup_f32 v108, v99, v98, 1.0
	s_and_b64 vcc, exec, s[10:11]
	v_pk_mul_f32 v[104:105], v[16:17], v[108:109] op_sel_hi:[1,0]
	v_pk_mul_f32 v[102:103], v[14:15], v[108:109] op_sel_hi:[1,0]
	v_pk_mul_f32 v[100:101], v[12:13], v[108:109] op_sel_hi:[1,0]
	v_pk_mul_f32 v[98:99], v[10:11], v[108:109] op_sel_hi:[1,0]
	v_pk_mul_f32 v[80:81], v[80:81], v[108:109] op_sel_hi:[1,0]
	v_pk_mul_f32 v[78:79], v[78:79], v[108:109] op_sel_hi:[1,0]
	v_pk_mul_f32 v[76:77], v[76:77], v[108:109] op_sel_hi:[1,0]
	v_pk_mul_f32 v[74:75], v[74:75], v[108:109] op_sel_hi:[1,0]
	s_cbranch_vccnz .LBB0_706
	v_pk_mul_f32 v[108:109], v[104:105], v[104:105]
	v_pk_mul_f32 v[110:111], v[102:103], v[102:103]
	s_nop 0
	v_pk_mov_b32 v[112:113], v[110:111], v[108:109] op_sel:[1,0]
	v_mov_b32_e32 v111, v109
	v_pk_add_f32 v[108:109], v[112:113], v[110:111]
	v_pk_mul_f32 v[110:111], v[100:101], v[100:101]
	v_pk_add_f32 v[108:109], v[108:109], v[108:109] op_sel_hi:[0,1]
	v_pk_mul_f32 v[112:113], v[98:99], v[98:99]
	v_mul_f32_e32 v108, v78, v78
	v_pk_mov_b32 v[114:115], v[112:113], v[110:111] op_sel:[1,0]
	v_mov_b32_e32 v113, v111
	v_pk_add_f32 v[110:111], v[114:115], v[112:113]
	v_pk_fma_f32 v[112:113], v[78:79], v[78:79], v[108:109] op_sel_hi:[1,1,0]
	v_mul_f32_e32 v108, v80, v80
	v_pk_add_f32 v[110:111], v[110:111], v[110:111] op_sel_hi:[0,1]
	v_pk_fma_f32 v[114:115], v[80:81], v[80:81], v[108:109] op_sel_hi:[1,1,0]
	v_mul_f32_e32 v112, v74, v74
	v_mul_f32_e32 v114, v75, v75
	v_mul_f32_e32 v108, v76, v76
	v_mul_f32_e32 v110, v77, v77
	v_pk_add_f32 v[112:113], v[112:113], v[114:115]
	v_pk_add_f32 v[108:109], v[108:109], v[110:111]
	s_nop 0
	v_pk_add_f32 v[108:109], v[112:113], v[108:109]
	s_nop 0
	v_add_f32_e32 v107, v108, v109
	v_and_b32_e32 v109, 64, v191
	v_xor_b32_e32 v108, 16, v191
	v_add_u32_e32 v109, 64, v109
	v_cmp_lt_i32_e32 vcc, v108, v109
	s_nop 1
	v_cndmask_b32_e32 v108, v191, v108, vcc
	v_lshlrev_b32_e32 v108, 2, v108
	ds_bpermute_b32 v108, v108, v107
	s_waitcnt lgkmcnt(0)
	v_add_f32_e32 v107, v107, v108
	v_xor_b32_e32 v108, 32, v191
	v_cmp_lt_i32_e32 vcc, v108, v109
	s_nop 1
	v_cndmask_b32_e32 v108, v191, v108, vcc
	v_lshlrev_b32_e32 v108, 2, v108
	ds_bpermute_b32 v108, v108, v107
	s_waitcnt lgkmcnt(0)
	v_add_f32_e32 v107, v107, v108
	v_fmamk_f32 v107, v107, 0x3c800000, v186
	v_mul_f32_e32 v108, 0x4f800000, v107
	v_cmp_gt_f32_e32 vcc, s58, v107
	s_nop 1
	v_cndmask_b32_e32 v107, v107, v108, vcc
	v_sqrt_f32_e32 v108, v107
	s_nop 0
	v_add_u32_e32 v109, -1, v108
	v_fma_f32 v110, -v109, v108, v107
	v_cmp_ge_f32_e64 s[16:17], 0, v110
	v_add_u32_e32 v110, 1, v108
	s_nop 0
	v_cndmask_b32_e64 v109, v108, v109, s[16:17]
	v_fma_f32 v108, -v110, v108, v107
	v_cmp_lt_f32_e64 s[16:17], 0, v108
	s_nop 1
	v_cndmask_b32_e64 v108, v109, v110, s[16:17]
	v_mul_f32_e32 v109, 0x37800000, v108
	v_cndmask_b32_e32 v108, v108, v109, vcc
	v_cmp_class_f32_e32 vcc, v107, v187
	s_nop 1
	v_cndmask_b32_e32 v107, v108, v107, vcc
	v_div_scale_f32 v108, s[2:3], v107, v107, 1.0
	v_rcp_f32_e32 v109, v108
	s_nop 0
	v_fma_f32 v110, -v108, v109, 1.0
	v_fmac_f32_e32 v109, v110, v109
	v_div_scale_f32 v110, vcc, 1.0, v107, 1.0
	v_mul_f32_e32 v111, v110, v109
	v_fma_f32 v112, -v108, v111, v110
	v_fmac_f32_e32 v111, v112, v109
	v_fma_f32 v108, -v108, v111, v110
	v_div_fmas_f32 v108, v108, v109, v111
	v_div_fixup_f32 v108, v108, v107, 1.0
	v_pk_mul_f32 v[102:103], v[102:103], v[108:109] op_sel_hi:[1,0]
	v_pk_mul_f32 v[104:105], v[104:105], v[108:109] op_sel_hi:[1,0]
	v_pk_mul_f32 v[98:99], v[98:99], v[108:109] op_sel_hi:[1,0]
	v_pk_mul_f32 v[100:101], v[100:101], v[108:109] op_sel_hi:[1,0]
	v_pk_mul_f32 v[78:79], v[78:79], v[108:109] op_sel_hi:[1,0]
	v_pk_mul_f32 v[80:81], v[80:81], v[108:109] op_sel_hi:[1,0]
	v_pk_mul_f32 v[74:75], v[74:75], v[108:109] op_sel_hi:[1,0]
	v_pk_mul_f32 v[76:77], v[76:77], v[108:109] op_sel_hi:[1,0]
	v_pk_mul_f32 v[104:105], v[88:89], v[104:105]
	v_pk_mul_f32 v[102:103], v[86:87], v[102:103]
	v_pk_mul_f32 v[100:101], v[84:85], v[100:101]
	v_pk_mul_f32 v[98:99], v[82:83], v[98:99]
	v_pk_mul_f32 v[80:81], v[96:97], v[80:81]
	v_pk_mul_f32 v[78:79], v[94:95], v[78:79]
	v_pk_mul_f32 v[76:77], v[92:93], v[76:77]
	v_pk_mul_f32 v[74:75], v[90:91], v[74:75]
	s_and_b64 vcc, exec, s[14:15]
	s_cbranch_vccz .LBB0_707

.LBB0_688:
	v_mov_b32_e32 v108, v182
	v_mov_b32_e32 v109, v182
	v_pk_mul_f32 v[102:103], v[182:183], v[102:103]
	v_pk_mul_f32 v[110:111], v[108:109], v[100:101]
	v_pk_mul_f32 v[100:101], v[182:183], v[98:99]
	v_cvt_pk_bf16_f32 v98, v102, v103
	v_mov_b64_e32 v[102:103], s[22:23]
	v_mad_i64_i32 v[102:103], s[2:3], v106, s60, v[102:103]
	v_lshl_add_u64 v[102:103], s[0:1], 1, v[102:103]
	v_pk_mul_f32 v[104:105], v[108:109], v[104:105]
	v_lshl_add_u64 v[102:103], v[102:103], 0, v[162:163]
	v_cvt_pk_bf16_f32 v99, v104, v105
	v_cvt_pk_bf16_f32 v100, v100, v101
	v_cvt_pk_bf16_f32 v101, v110, v111
	global_store_dwordx4 v[102:103], v[98:101], off
	v_pk_mul_f32 v[80:81], v[108:109], v[80:81]
	v_pk_mul_f32 v[78:79], v[182:183], v[78:79]
	v_pk_mul_f32 v[98:99], v[108:109], v[76:77]
	v_pk_mul_f32 v[76:77], v[182:183], v[74:75]
	v_cvt_pk_bf16_f32 v74, v78, v79
	v_cvt_pk_bf16_f32 v75, v80, v81
	s_nop 0
	v_cvt_pk_bf16_f32 v76, v76, v77
	v_cvt_pk_bf16_f32 v77, v98, v99
	v_add_u32_e32 v98, 0xb0, v180
	v_ashrrev_i32_e32 v99, 31, v98
	global_store_dwordx4 v[102:103], v[74:77], off offset:64
	s_nop 1
	v_lshlrev_b64 v[74:75], 6, v[98:99]
	v_lshl_add_u64 v[104:105], s[24:25], 0, v[74:75]
	global_load_dwordx4 v[74:77], v[104:105], off
	global_load_dwordx4 v[78:81], v[104:105], off offset:16
	global_load_dwordx4 v[100:103], v[104:105], off offset:32
	s_nop 0
	global_load_dwordx4 v[104:107], v[104:105], off offset:48
	s_waitcnt vmcnt(3)
	v_mov_b32_e32 v108, v75
	v_mov_b32_e32 v109, v76
	v_mov_b32_e32 v75, v77
	s_waitcnt vmcnt(2)
	v_mov_b32_e32 v76, v79
	v_mov_b32_e32 v77, v80
	v_mov_b32_e32 v79, v81
	v_pk_add_f32 v[74:75], v[108:109], v[74:75]
	v_pk_add_f32 v[76:77], v[76:77], v[78:79]
	v_pk_add_f32 v[74:75], v[74:75], v[74:75] op_sel:[0,1] op_sel_hi:[1,0]
	v_pk_add_f32 v[76:77], v[76:77], v[76:77] op_sel:[0,1] op_sel_hi:[1,0]
	s_waitcnt vmcnt(1)
	v_add_f32_e32 v80, v100, v101
	v_add_f32_e32 v100, v102, v103
	s_waitcnt vmcnt(0)
	v_mov_b32_e32 v81, v106
	v_mov_b32_e32 v101, v107
	v_mov_b32_e32 v75, v104
	v_mov_b32_e32 v77, v105
	v_pk_add_f32 v[78:79], v[80:81], v[100:101]
	v_pk_add_f32 v[74:75], v[74:75], v[76:77]
	s_nop 0
	v_pk_add_f32 v[74:75], v[74:75], v[78:79]
	s_nop 0
	v_add_f32_e32 v74, v74, v75
	v_fmamk_f32 v74, v74, 0x3a800000, v186
	v_mul_f32_e32 v75, 0x4f800000, v74
	v_cmp_gt_f32_e32 vcc, s58, v74
	s_nop 1
	v_cndmask_b32_e32 v74, v74, v75, vcc
	v_sqrt_f32_e32 v75, v74
	s_nop 0
	v_add_u32_e32 v76, -1, v75
	v_add_u32_e32 v77, 1, v75
	v_fma_f32 v78, -v76, v75, v74
	v_fma_f32 v79, -v77, v75, v74
	v_cmp_ge_f32_e64 s[16:17], 0, v78
	s_nop 1
	v_cndmask_b32_e64 v75, v75, v76, s[16:17]
	v_cmp_lt_f32_e64 s[16:17], 0, v79
	s_nop 1
	v_cndmask_b32_e64 v75, v75, v77, s[16:17]
	v_mul_f32_e32 v76, 0x37800000, v75
	v_cndmask_b32_e32 v75, v75, v76, vcc
	v_cmp_class_f32_e32 vcc, v74, v187
	s_nop 1
	v_cndmask_b32_e32 v74, v75, v74, vcc
	v_div_scale_f32 v75, s[2:3], v74, v74, 1.0
	v_rcp_f32_e32 v76, v75
	v_div_scale_f32 v77, vcc, 1.0, v74, 1.0
	v_fma_f32 v78, -v75, v76, 1.0
	v_fmac_f32_e32 v76, v78, v76
	v_mul_f32_e32 v78, v77, v76
	v_fma_f32 v79, -v75, v78, v77
	v_fmac_f32_e32 v78, v79, v76
	v_fma_f32 v75, -v75, v78, v77
	v_div_fmas_f32 v75, v75, v76, v78
	v_div_fixup_f32 v100, v75, v74, 1.0
	s_and_b64 vcc, exec, s[10:11]
	v_pk_mul_f32 v[80:81], v[8:9], v[100:101] op_sel_hi:[1,0]
	v_pk_mul_f32 v[78:79], v[6:7], v[100:101] op_sel_hi:[1,0]
	v_pk_mul_f32 v[76:77], v[4:5], v[100:101] op_sel_hi:[1,0]
	v_pk_mul_f32 v[74:75], v[2:3], v[100:101] op_sel_hi:[1,0]
	v_pk_mul_f32 v[72:73], v[72:73], v[100:101] op_sel_hi:[1,0]
	v_pk_mul_f32 v[70:71], v[70:71], v[100:101] op_sel_hi:[1,0]
	v_pk_mul_f32 v[68:69], v[68:69], v[100:101] op_sel_hi:[1,0]
	v_pk_mul_f32 v[66:67], v[66:67], v[100:101] op_sel_hi:[1,0]
	s_cbranch_vccnz .LBB0_708
	v_pk_mul_f32 v[100:101], v[80:81], v[80:81]
	v_pk_mul_f32 v[102:103], v[78:79], v[78:79]
	s_nop 0
	v_pk_mov_b32 v[104:105], v[102:103], v[100:101] op_sel:[1,0]
	v_mov_b32_e32 v103, v101
	v_pk_add_f32 v[100:101], v[104:105], v[102:103]
	v_pk_mul_f32 v[102:103], v[76:77], v[76:77]
	v_pk_add_f32 v[100:101], v[100:101], v[100:101] op_sel_hi:[0,1]
	v_pk_mul_f32 v[104:105], v[74:75], v[74:75]
	v_mul_f32_e32 v100, v70, v70
	v_pk_mov_b32 v[106:107], v[104:105], v[102:103] op_sel:[1,0]
	v_mov_b32_e32 v105, v103
	v_pk_add_f32 v[102:103], v[106:107], v[104:105]
	v_pk_fma_f32 v[104:105], v[70:71], v[70:71], v[100:101] op_sel_hi:[1,1,0]
	v_mul_f32_e32 v100, v72, v72
	v_pk_add_f32 v[102:103], v[102:103], v[102:103] op_sel_hi:[0,1]
	v_pk_fma_f32 v[106:107], v[72:73], v[72:73], v[100:101] op_sel_hi:[1,1,0]
	v_mul_f32_e32 v104, v66, v66
	v_mul_f32_e32 v106, v67, v67
	v_mul_f32_e32 v100, v68, v68
	v_mul_f32_e32 v102, v69, v69
	v_pk_add_f32 v[104:105], v[104:105], v[106:107]
	v_pk_add_f32 v[100:101], v[100:101], v[102:103]
	s_nop 0
	v_pk_add_f32 v[100:101], v[104:105], v[100:101]
	s_nop 0
	v_add_f32_e32 v99, v100, v101
	v_and_b32_e32 v101, 64, v191
	v_xor_b32_e32 v100, 16, v191
	v_add_u32_e32 v101, 64, v101
	v_cmp_lt_i32_e32 vcc, v100, v101
	s_nop 1
	v_cndmask_b32_e32 v100, v191, v100, vcc
	v_lshlrev_b32_e32 v100, 2, v100
	ds_bpermute_b32 v100, v100, v99
	s_waitcnt lgkmcnt(0)
	v_add_f32_e32 v99, v99, v100
	v_xor_b32_e32 v100, 32, v191
	v_cmp_lt_i32_e32 vcc, v100, v101
	s_nop 1
	v_cndmask_b32_e32 v100, v191, v100, vcc
	v_lshlrev_b32_e32 v100, 2, v100
	ds_bpermute_b32 v100, v100, v99
	s_waitcnt lgkmcnt(0)
	v_add_f32_e32 v99, v99, v100
	v_fmamk_f32 v99, v99, 0x3c800000, v186
	v_mul_f32_e32 v100, 0x4f800000, v99
	v_cmp_gt_f32_e32 vcc, s58, v99
	s_nop 1
	v_cndmask_b32_e32 v99, v99, v100, vcc
	v_sqrt_f32_e32 v100, v99
	s_nop 0
	v_add_u32_e32 v101, -1, v100
	v_fma_f32 v102, -v101, v100, v99
	v_cmp_ge_f32_e64 s[10:11], 0, v102
	v_add_u32_e32 v102, 1, v100
	s_nop 0
	v_cndmask_b32_e64 v101, v100, v101, s[10:11]
	v_fma_f32 v100, -v102, v100, v99
	v_cmp_lt_f32_e64 s[10:11], 0, v100
	s_nop 1
	v_cndmask_b32_e64 v100, v101, v102, s[10:11]
	v_mul_f32_e32 v101, 0x37800000, v100
	v_cndmask_b32_e32 v100, v100, v101, vcc
	v_cmp_class_f32_e32 vcc, v99, v187
	s_nop 1
	v_cndmask_b32_e32 v99, v100, v99, vcc
	v_div_scale_f32 v100, s[2:3], v99, v99, 1.0
	v_rcp_f32_e32 v101, v100
	s_nop 0
	v_fma_f32 v102, -v100, v101, 1.0
	v_fmac_f32_e32 v101, v102, v101
	v_div_scale_f32 v102, vcc, 1.0, v99, 1.0
	v_mul_f32_e32 v103, v102, v101
	v_fma_f32 v104, -v100, v103, v102
	v_fmac_f32_e32 v103, v104, v101
	v_fma_f32 v100, -v100, v103, v102
	v_div_fmas_f32 v100, v100, v101, v103
	v_div_fixup_f32 v100, v100, v99, 1.0
	v_pk_mul_f32 v[78:79], v[78:79], v[100:101] op_sel_hi:[1,0]
	v_pk_mul_f32 v[80:81], v[80:81], v[100:101] op_sel_hi:[1,0]
	v_pk_mul_f32 v[74:75], v[74:75], v[100:101] op_sel_hi:[1,0]
	v_pk_mul_f32 v[76:77], v[76:77], v[100:101] op_sel_hi:[1,0]
	v_pk_mul_f32 v[70:71], v[70:71], v[100:101] op_sel_hi:[1,0]
	v_pk_mul_f32 v[72:73], v[72:73], v[100:101] op_sel_hi:[1,0]
	v_pk_mul_f32 v[66:67], v[66:67], v[100:101] op_sel_hi:[1,0]
	v_pk_mul_f32 v[68:69], v[68:69], v[100:101] op_sel_hi:[1,0]
	v_pk_mul_f32 v[80:81], v[88:89], v[80:81]
	v_pk_mul_f32 v[78:79], v[86:87], v[78:79]
	v_pk_mul_f32 v[76:77], v[84:85], v[76:77]
	v_pk_mul_f32 v[74:75], v[82:83], v[74:75]
	v_pk_mul_f32 v[72:73], v[96:97], v[72:73]
	v_pk_mul_f32 v[70:71], v[94:95], v[70:71]
	v_pk_mul_f32 v[68:69], v[92:93], v[68:69]
	v_pk_mul_f32 v[66:67], v[90:91], v[66:67]
	s_and_b64 vcc, exec, s[14:15]
	s_cbranch_vccz .LBB0_709

.LBB0_692:
	v_mov_b32_e32 v82, v182
	v_mov_b32_e32 v83, v182
	v_pk_mul_f32 v[78:79], v[182:183], v[78:79]
	v_pk_mul_f32 v[84:85], v[82:83], v[76:77]
	v_pk_mul_f32 v[76:77], v[182:183], v[74:75]
	v_cvt_pk_bf16_f32 v74, v78, v79
	v_mov_b64_e32 v[78:79], s[22:23]
	v_mad_i64_i32 v[78:79], s[2:3], v98, s60, v[78:79]
	v_lshl_add_u64 v[78:79], s[0:1], 1, v[78:79]
	v_pk_mul_f32 v[80:81], v[82:83], v[80:81]
	v_lshl_add_u64 v[78:79], v[78:79], 0, v[162:163]
	v_cvt_pk_bf16_f32 v75, v80, v81
	v_cvt_pk_bf16_f32 v76, v76, v77
	v_cvt_pk_bf16_f32 v77, v84, v85
	global_store_dwordx4 v[78:79], v[74:77], off
	v_pk_mul_f32 v[72:73], v[82:83], v[72:73]
	s_nop 0
	v_pk_mul_f32 v[74:75], v[82:83], v[68:69]
	v_pk_mul_f32 v[68:69], v[182:183], v[66:67]
	v_pk_mul_f32 v[70:71], v[182:183], v[70:71]
	s_nop 0
	v_cvt_pk_bf16_f32 v66, v70, v71
	v_cvt_pk_bf16_f32 v67, v72, v73
	v_cvt_pk_bf16_f32 v68, v68, v69
	v_cvt_pk_bf16_f32 v69, v74, v75
	global_store_dwordx4 v[78:79], v[66:69], off offset:64

.LBB0_2925:
	s_bitcmp0_b32 s15, 2
	s_cselect_b64 s[0:1], -1, 0
	v_cndmask_b32_e64 v182, v192, 1.0, s[0:1]
	v_pk_mul_f32 v[150:151], v[182:183], v[150:151] op_sel_hi:[0,1]
	s_lshl_b32 s0, s14, 6
	v_pk_mul_f32 v[194:195], v[182:183], v[148:149] op_sel_hi:[0,1]
	v_pk_mul_f32 v[148:149], v[182:183], v[146:147] op_sel_hi:[0,1]
	v_cvt_pk_bf16_f32 v146, v150, v151
	v_mov_b64_e32 v[150:151], s[22:23]
	s_ashr_i32 s1, s0, 31
	v_mad_i64_i32 v[150:151], s[14:15], v180, s72, v[150:151]
	v_lshl_add_u64 v[150:151], s[0:1], 1, v[150:151]
	v_lshlrev_b32_e32 v162, 1, v164
	v_pk_mul_f32 v[152:153], v[182:183], v[152:153] op_sel_hi:[0,1]
	v_cvt_pk_bf16_f32 v147, v152, v153
	v_lshl_add_u64 v[150:151], v[150:151], 0, v[162:163]
	v_cvt_pk_bf16_f32 v148, v148, v149
	v_cvt_pk_bf16_f32 v149, v194, v195
	global_store_dwordx4 v[150:151], v[146:149], off
	v_pk_mul_f32 v[144:145], v[182:183], v[144:145] op_sel_hi:[0,1]
	v_pk_mul_f32 v[142:143], v[182:183], v[142:143] op_sel_hi:[0,1]
	v_pk_mul_f32 v[146:147], v[182:183], v[140:141] op_sel_hi:[0,1]
	v_pk_mul_f32 v[140:141], v[182:183], v[138:139] op_sel_hi:[0,1]
	v_cvt_pk_bf16_f32 v138, v142, v143
	v_cvt_pk_bf16_f32 v139, v144, v145
	v_cvt_pk_bf16_f32 v140, v140, v141
	v_cvt_pk_bf16_f32 v141, v146, v147
	v_or_b32_e32 v146, 16, v180
	v_ashrrev_i32_e32 v147, 31, v146
	global_store_dwordx4 v[150:151], v[138:141], off offset:64
	s_nop 1
	v_lshlrev_b64 v[138:139], 6, v[146:147]
	v_lshl_add_u64 v[152:153], s[36:37], 0, v[138:139]
	global_load_dwordx4 v[138:141], v[152:153], off
	global_load_dwordx4 v[142:145], v[152:153], off offset:16
	global_load_dwordx4 v[148:151], v[152:153], off offset:32
	global_load_dwordx4 v[194:197], v[152:153], off offset:48
	s_waitcnt vmcnt(3)
	v_mov_b32_e32 v152, v139
	v_mov_b32_e32 v153, v140
	v_mov_b32_e32 v139, v141
	s_waitcnt vmcnt(2)
	v_mov_b32_e32 v140, v143
	v_mov_b32_e32 v141, v144
	v_mov_b32_e32 v143, v145
	v_pk_add_f32 v[138:139], v[152:153], v[138:139]
	v_pk_add_f32 v[140:141], v[140:141], v[142:143]
	v_pk_add_f32 v[138:139], v[138:139], v[138:139] op_sel:[0,1] op_sel_hi:[1,0]
	v_pk_add_f32 v[140:141], v[140:141], v[140:141] op_sel:[0,1] op_sel_hi:[1,0]
	s_waitcnt vmcnt(1)
	v_add_f32_e32 v144, v148, v149
	v_add_f32_e32 v148, v150, v151
	s_waitcnt vmcnt(0)
	v_mov_b32_e32 v145, v196
	v_mov_b32_e32 v149, v197
	v_mov_b32_e32 v139, v194
	v_mov_b32_e32 v141, v195
	v_pk_add_f32 v[142:143], v[144:145], v[148:149]
	v_pk_add_f32 v[138:139], v[138:139], v[140:141]
	s_nop 0
	v_pk_add_f32 v[138:139], v[138:139], v[142:143]
	s_nop 0
	v_add_f32_e32 v138, v138, v139
	v_fmamk_f32 v138, v138, 0x3a800000, v186
	v_mul_f32_e32 v139, 0x4f800000, v138
	v_cmp_gt_f32_e32 vcc, s70, v138
	s_nop 1
	v_cndmask_b32_e32 v138, v138, v139, vcc
	v_sqrt_f32_e32 v139, v138
	s_nop 0
	v_add_u32_e32 v140, -1, v139
	v_add_u32_e32 v141, 1, v139
	v_fma_f32 v142, -v140, v139, v138
	v_fma_f32 v143, -v141, v139, v138
	v_cmp_ge_f32_e64 s[14:15], 0, v142
	s_nop 1
	v_cndmask_b32_e64 v139, v139, v140, s[14:15]
	v_cmp_lt_f32_e64 s[14:15], 0, v143
	s_nop 1
	v_cndmask_b32_e64 v139, v139, v141, s[14:15]
	v_mul_f32_e32 v140, 0x37800000, v139
	v_cndmask_b32_e32 v139, v139, v140, vcc
	v_cmp_class_f32_e32 vcc, v138, v187
	s_nop 1
	v_cndmask_b32_e32 v138, v139, v138, vcc
	v_div_scale_f32 v139, s[14:15], v138, v138, 1.0
	v_rcp_f32_e32 v140, v139
	v_div_scale_f32 v141, vcc, 1.0, v138, 1.0
	v_fma_f32 v142, -v139, v140, 1.0
	v_fmac_f32_e32 v140, v142, v140
	v_mul_f32_e32 v142, v141, v140
	v_fma_f32 v143, -v139, v142, v141
	v_fmac_f32_e32 v142, v143, v140
	v_fma_f32 v139, -v139, v142, v141
	v_div_fmas_f32 v139, v139, v140, v142
	v_div_fixup_f32 v148, v139, v138, 1.0
	s_and_b64 vcc, exec, s[10:11]
	v_pk_mul_f32 v[144:145], v[56:57], v[148:149] op_sel_hi:[1,0]
	v_pk_mul_f32 v[142:143], v[54:55], v[148:149] op_sel_hi:[1,0]
	v_pk_mul_f32 v[140:141], v[52:53], v[148:149] op_sel_hi:[1,0]
	v_pk_mul_f32 v[138:139], v[50:51], v[148:149] op_sel_hi:[1,0]
	v_pk_mul_f32 v[136:137], v[136:137], v[148:149] op_sel_hi:[1,0]
	v_pk_mul_f32 v[134:135], v[134:135], v[148:149] op_sel_hi:[1,0]
	v_pk_mul_f32 v[132:133], v[132:133], v[148:149] op_sel_hi:[1,0]
	v_pk_mul_f32 v[130:131], v[130:131], v[148:149] op_sel_hi:[1,0]
	s_cbranch_vccnz .LBB0_2957
	v_pk_mul_f32 v[148:149], v[144:145], v[144:145]
	v_pk_mul_f32 v[150:151], v[142:143], v[142:143]
	s_nop 0
	v_pk_mov_b32 v[152:153], v[150:151], v[148:149] op_sel:[1,0]
	v_mov_b32_e32 v151, v149
	v_pk_add_f32 v[148:149], v[152:153], v[150:151]
	v_pk_mul_f32 v[150:151], v[140:141], v[140:141]
	v_pk_add_f32 v[148:149], v[148:149], v[148:149] op_sel_hi:[0,1]
	v_pk_mul_f32 v[152:153], v[138:139], v[138:139]
	v_mul_f32_e32 v148, v134, v134
	v_pk_mov_b32 v[194:195], v[152:153], v[150:151] op_sel:[1,0]
	v_mov_b32_e32 v153, v151
	v_pk_add_f32 v[150:151], v[194:195], v[152:153]
	v_pk_fma_f32 v[152:153], v[134:135], v[134:135], v[148:149] op_sel_hi:[1,1,0]
	v_mul_f32_e32 v148, v136, v136
	v_pk_add_f32 v[150:151], v[150:151], v[150:151] op_sel_hi:[0,1]
	v_pk_fma_f32 v[194:195], v[136:137], v[136:137], v[148:149] op_sel_hi:[1,1,0]
	v_mul_f32_e32 v152, v130, v130
	v_mul_f32_e32 v194, v131, v131
	v_mul_f32_e32 v148, v132, v132
	v_mul_f32_e32 v150, v133, v133
	v_pk_add_f32 v[152:153], v[152:153], v[194:195]
	v_pk_add_f32 v[148:149], v[148:149], v[150:151]
	s_nop 0
	v_pk_add_f32 v[148:149], v[152:153], v[148:149]
	s_nop 0
	v_add_f32_e32 v147, v148, v149
	v_and_b32_e32 v149, 64, v191
	v_xor_b32_e32 v148, 16, v191
	v_add_u32_e32 v149, 64, v149
	v_cmp_lt_i32_e32 vcc, v148, v149
	s_nop 1
	v_cndmask_b32_e32 v148, v191, v148, vcc
	v_lshlrev_b32_e32 v148, 2, v148
	ds_bpermute_b32 v148, v148, v147
	s_waitcnt lgkmcnt(0)
	v_add_f32_e32 v147, v147, v148
	v_xor_b32_e32 v148, 32, v191
	v_cmp_lt_i32_e32 vcc, v148, v149
	s_nop 1
	v_cndmask_b32_e32 v148, v191, v148, vcc
	v_lshlrev_b32_e32 v148, 2, v148
	ds_bpermute_b32 v148, v148, v147
	s_waitcnt lgkmcnt(0)
	v_add_f32_e32 v147, v147, v148
	v_fmamk_f32 v147, v147, 0x3c800000, v186
	v_mul_f32_e32 v148, 0x4f800000, v147
	v_cmp_gt_f32_e32 vcc, s70, v147
	s_nop 1
	v_cndmask_b32_e32 v147, v147, v148, vcc
	v_sqrt_f32_e32 v148, v147
	s_nop 0
	v_add_u32_e32 v149, -1, v148
	v_fma_f32 v150, -v149, v148, v147
	v_cmp_ge_f32_e64 s[14:15], 0, v150
	v_add_u32_e32 v150, 1, v148
	s_nop 0
	v_cndmask_b32_e64 v149, v148, v149, s[14:15]
	v_fma_f32 v148, -v150, v148, v147
	v_cmp_lt_f32_e64 s[14:15], 0, v148
	s_nop 1
	v_cndmask_b32_e64 v148, v149, v150, s[14:15]
	v_mul_f32_e32 v149, 0x37800000, v148
	v_cndmask_b32_e32 v148, v148, v149, vcc
	v_cmp_class_f32_e32 vcc, v147, v187
	s_nop 1
	v_cndmask_b32_e32 v147, v148, v147, vcc
	v_div_scale_f32 v148, s[14:15], v147, v147, 1.0
	v_rcp_f32_e32 v149, v148
	s_nop 0
	v_fma_f32 v150, -v148, v149, 1.0
	v_fmac_f32_e32 v149, v150, v149
	v_div_scale_f32 v150, vcc, 1.0, v147, 1.0
	v_mul_f32_e32 v151, v150, v149
	v_fma_f32 v152, -v148, v151, v150
	v_fmac_f32_e32 v151, v152, v149
	v_fma_f32 v148, -v148, v151, v150
	v_div_fmas_f32 v148, v148, v149, v151
	v_div_fixup_f32 v148, v148, v147, 1.0
	v_pk_mul_f32 v[142:143], v[142:143], v[148:149] op_sel_hi:[1,0]
	v_pk_mul_f32 v[144:145], v[144:145], v[148:149] op_sel_hi:[1,0]
	v_pk_mul_f32 v[138:139], v[138:139], v[148:149] op_sel_hi:[1,0]
	v_pk_mul_f32 v[140:141], v[140:141], v[148:149] op_sel_hi:[1,0]
	v_pk_mul_f32 v[134:135], v[134:135], v[148:149] op_sel_hi:[1,0]
	v_pk_mul_f32 v[136:137], v[136:137], v[148:149] op_sel_hi:[1,0]
	v_pk_mul_f32 v[130:131], v[130:131], v[148:149] op_sel_hi:[1,0]
	v_pk_mul_f32 v[132:133], v[132:133], v[148:149] op_sel_hi:[1,0]
	v_pk_mul_f32 v[144:145], v[88:89], v[144:145]
	v_pk_mul_f32 v[142:143], v[86:87], v[142:143]
	v_pk_mul_f32 v[140:141], v[84:85], v[140:141]
	v_pk_mul_f32 v[138:139], v[82:83], v[138:139]
	v_pk_mul_f32 v[136:137], v[96:97], v[136:137]
	v_pk_mul_f32 v[134:135], v[94:95], v[134:135]
	v_pk_mul_f32 v[132:133], v[92:93], v[132:133]
	v_pk_mul_f32 v[130:131], v[90:91], v[130:131]
	v_cndmask_b32_e64 v147, 0, 1, s[2:3]
	v_cmp_ne_u32_e64 s[14:15], 1, v147
	s_andn2_b64 vcc, exec, s[2:3]
	s_cbranch_vccz .LBB0_2958

.LBB0_2929:
	v_mov_b32_e32 v183, v182
	v_mov_b32_e32 v148, v182
	v_mov_b32_e32 v149, v182
	v_pk_mul_f32 v[142:143], v[182:183], v[142:143]
	v_pk_mul_f32 v[150:151], v[148:149], v[140:141]
	v_pk_mul_f32 v[140:141], v[182:183], v[138:139]
	v_cvt_pk_bf16_f32 v138, v142, v143
	v_mov_b64_e32 v[142:143], s[22:23]
	v_mad_i64_i32 v[142:143], s[2:3], v146, s72, v[142:143]
	v_lshl_add_u64 v[142:143], s[0:1], 1, v[142:143]
	v_pk_mul_f32 v[144:145], v[148:149], v[144:145]
	v_lshl_add_u64 v[142:143], v[142:143], 0, v[162:163]
	v_cvt_pk_bf16_f32 v139, v144, v145
	v_cvt_pk_bf16_f32 v140, v140, v141
	v_cvt_pk_bf16_f32 v141, v150, v151
	global_store_dwordx4 v[142:143], v[138:141], off
	v_pk_mul_f32 v[136:137], v[148:149], v[136:137]
	v_pk_mul_f32 v[134:135], v[182:183], v[134:135]
	v_pk_mul_f32 v[138:139], v[148:149], v[132:133]
	v_pk_mul_f32 v[132:133], v[182:183], v[130:131]
	v_cvt_pk_bf16_f32 v130, v134, v135
	v_cvt_pk_bf16_f32 v131, v136, v137
	s_nop 0
	v_cvt_pk_bf16_f32 v132, v132, v133
	v_cvt_pk_bf16_f32 v133, v138, v139
	v_or_b32_e32 v138, 32, v180
	v_ashrrev_i32_e32 v139, 31, v138
	global_store_dwordx4 v[142:143], v[130:133], off offset:64
	s_nop 1
	v_lshlrev_b64 v[130:131], 6, v[138:139]
	v_lshl_add_u64 v[144:145], s[36:37], 0, v[130:131]
	global_load_dwordx4 v[130:133], v[144:145], off
	global_load_dwordx4 v[134:137], v[144:145], off offset:16
	global_load_dwordx4 v[140:143], v[144:145], off offset:32
	s_nop 0
	global_load_dwordx4 v[144:147], v[144:145], off offset:48
	s_waitcnt vmcnt(3)
	v_mov_b32_e32 v148, v131
	v_mov_b32_e32 v149, v132
	v_mov_b32_e32 v131, v133
	s_waitcnt vmcnt(2)
	v_mov_b32_e32 v132, v135
	v_mov_b32_e32 v133, v136
	v_mov_b32_e32 v135, v137
	v_pk_add_f32 v[130:131], v[148:149], v[130:131]
	v_pk_add_f32 v[132:133], v[132:133], v[134:135]
	v_pk_add_f32 v[130:131], v[130:131], v[130:131] op_sel:[0,1] op_sel_hi:[1,0]
	v_pk_add_f32 v[132:133], v[132:133], v[132:133] op_sel:[0,1] op_sel_hi:[1,0]
	s_waitcnt vmcnt(1)
	v_add_f32_e32 v136, v140, v141
	v_add_f32_e32 v140, v142, v143
	s_waitcnt vmcnt(0)
	v_mov_b32_e32 v137, v146
	v_mov_b32_e32 v141, v147
	v_mov_b32_e32 v131, v144
	v_mov_b32_e32 v133, v145
	v_pk_add_f32 v[134:135], v[136:137], v[140:141]
	v_pk_add_f32 v[130:131], v[130:131], v[132:133]
	s_nop 0
	v_pk_add_f32 v[130:131], v[130:131], v[134:135]
	s_nop 0
	v_add_f32_e32 v130, v130, v131
	v_fmamk_f32 v130, v130, 0x3a800000, v186
	v_mul_f32_e32 v131, 0x4f800000, v130
	v_cmp_gt_f32_e32 vcc, s70, v130
	s_nop 1
	v_cndmask_b32_e32 v130, v130, v131, vcc
	v_sqrt_f32_e32 v131, v130
	s_nop 0
	v_add_u32_e32 v132, -1, v131
	v_add_u32_e32 v133, 1, v131
	v_fma_f32 v134, -v132, v131, v130
	v_fma_f32 v135, -v133, v131, v130
	v_cmp_ge_f32_e64 s[16:17], 0, v134
	s_nop 1
	v_cndmask_b32_e64 v131, v131, v132, s[16:17]
	v_cmp_lt_f32_e64 s[16:17], 0, v135
	s_nop 1
	v_cndmask_b32_e64 v131, v131, v133, s[16:17]
	v_mul_f32_e32 v132, 0x37800000, v131
	v_cndmask_b32_e32 v131, v131, v132, vcc
	v_cmp_class_f32_e32 vcc, v130, v187
	s_nop 1
	v_cndmask_b32_e32 v130, v131, v130, vcc
	v_div_scale_f32 v131, s[2:3], v130, v130, 1.0
	v_rcp_f32_e32 v132, v131
	v_div_scale_f32 v133, vcc, 1.0, v130, 1.0
	v_fma_f32 v134, -v131, v132, 1.0
	v_fmac_f32_e32 v132, v134, v132
	v_mul_f32_e32 v134, v133, v132
	v_fma_f32 v135, -v131, v134, v133
	v_fmac_f32_e32 v134, v135, v132
	v_fma_f32 v131, -v131, v134, v133
	v_div_fmas_f32 v131, v131, v132, v134
	v_div_fixup_f32 v140, v131, v130, 1.0
	s_and_b64 vcc, exec, s[10:11]
	v_pk_mul_f32 v[136:137], v[48:49], v[140:141] op_sel_hi:[1,0]
	v_pk_mul_f32 v[134:135], v[46:47], v[140:141] op_sel_hi:[1,0]
	v_pk_mul_f32 v[132:133], v[44:45], v[140:141] op_sel_hi:[1,0]
	v_pk_mul_f32 v[130:131], v[42:43], v[140:141] op_sel_hi:[1,0]
	v_pk_mul_f32 v[128:129], v[128:129], v[140:141] op_sel_hi:[1,0]
	v_pk_mul_f32 v[126:127], v[126:127], v[140:141] op_sel_hi:[1,0]
	v_pk_mul_f32 v[124:125], v[124:125], v[140:141] op_sel_hi:[1,0]
	v_pk_mul_f32 v[122:123], v[122:123], v[140:141] op_sel_hi:[1,0]
	s_cbranch_vccnz .LBB0_2959
	v_pk_mul_f32 v[140:141], v[136:137], v[136:137]
	v_pk_mul_f32 v[142:143], v[134:135], v[134:135]
	s_nop 0
	v_pk_mov_b32 v[144:145], v[142:143], v[140:141] op_sel:[1,0]
	v_mov_b32_e32 v143, v141
	v_pk_add_f32 v[140:141], v[144:145], v[142:143]
	v_pk_mul_f32 v[142:143], v[132:133], v[132:133]
	v_pk_add_f32 v[140:141], v[140:141], v[140:141] op_sel_hi:[0,1]
	v_pk_mul_f32 v[144:145], v[130:131], v[130:131]
	v_mul_f32_e32 v140, v126, v126
	v_pk_mov_b32 v[146:147], v[144:145], v[142:143] op_sel:[1,0]
	v_mov_b32_e32 v145, v143
	v_pk_add_f32 v[142:143], v[146:147], v[144:145]
	v_pk_fma_f32 v[144:145], v[126:127], v[126:127], v[140:141] op_sel_hi:[1,1,0]
	v_mul_f32_e32 v140, v128, v128
	v_pk_add_f32 v[142:143], v[142:143], v[142:143] op_sel_hi:[0,1]
	v_pk_fma_f32 v[146:147], v[128:129], v[128:129], v[140:141] op_sel_hi:[1,1,0]
	v_mul_f32_e32 v144, v122, v122
	v_mul_f32_e32 v146, v123, v123
	v_mul_f32_e32 v140, v124, v124
	v_mul_f32_e32 v142, v125, v125
	v_pk_add_f32 v[144:145], v[144:145], v[146:147]
	v_pk_add_f32 v[140:141], v[140:141], v[142:143]
	s_nop 0
	v_pk_add_f32 v[140:141], v[144:145], v[140:141]
	s_nop 0
	v_add_f32_e32 v139, v140, v141
	v_and_b32_e32 v141, 64, v191
	v_xor_b32_e32 v140, 16, v191
	v_add_u32_e32 v141, 64, v141
	v_cmp_lt_i32_e32 vcc, v140, v141
	s_nop 1
	v_cndmask_b32_e32 v140, v191, v140, vcc
	v_lshlrev_b32_e32 v140, 2, v140
	ds_bpermute_b32 v140, v140, v139
	s_waitcnt lgkmcnt(0)
	v_add_f32_e32 v139, v139, v140
	v_xor_b32_e32 v140, 32, v191
	v_cmp_lt_i32_e32 vcc, v140, v141
	s_nop 1
	v_cndmask_b32_e32 v140, v191, v140, vcc
	v_lshlrev_b32_e32 v140, 2, v140
	ds_bpermute_b32 v140, v140, v139
	s_waitcnt lgkmcnt(0)
	v_add_f32_e32 v139, v139, v140
	v_fmamk_f32 v139, v139, 0x3c800000, v186
	v_mul_f32_e32 v140, 0x4f800000, v139
	v_cmp_gt_f32_e32 vcc, s70, v139
	s_nop 1
	v_cndmask_b32_e32 v139, v139, v140, vcc
	v_sqrt_f32_e32 v140, v139
	s_nop 0
	v_add_u32_e32 v141, -1, v140
	v_fma_f32 v142, -v141, v140, v139
	v_cmp_ge_f32_e64 s[16:17], 0, v142
	v_add_u32_e32 v142, 1, v140
	s_nop 0
	v_cndmask_b32_e64 v141, v140, v141, s[16:17]
	v_fma_f32 v140, -v142, v140, v139
	v_cmp_lt_f32_e64 s[16:17], 0, v140
	s_nop 1
	v_cndmask_b32_e64 v140, v141, v142, s[16:17]
	v_mul_f32_e32 v141, 0x37800000, v140
	v_cndmask_b32_e32 v140, v140, v141, vcc
	v_cmp_class_f32_e32 vcc, v139, v187
	s_nop 1
	v_cndmask_b32_e32 v139, v140, v139, vcc
	v_div_scale_f32 v140, s[2:3], v139, v139, 1.0
	v_rcp_f32_e32 v141, v140
	s_nop 0
	v_fma_f32 v142, -v140, v141, 1.0
	v_fmac_f32_e32 v141, v142, v141
	v_div_scale_f32 v142, vcc, 1.0, v139, 1.0
	v_mul_f32_e32 v143, v142, v141
	v_fma_f32 v144, -v140, v143, v142
	v_fmac_f32_e32 v143, v144, v141
	v_fma_f32 v140, -v140, v143, v142
	v_div_fmas_f32 v140, v140, v141, v143
	v_div_fixup_f32 v140, v140, v139, 1.0
	v_pk_mul_f32 v[134:135], v[134:135], v[140:141] op_sel_hi:[1,0]
	v_pk_mul_f32 v[136:137], v[136:137], v[140:141] op_sel_hi:[1,0]
	v_pk_mul_f32 v[130:131], v[130:131], v[140:141] op_sel_hi:[1,0]
	v_pk_mul_f32 v[132:133], v[132:133], v[140:141] op_sel_hi:[1,0]
	v_pk_mul_f32 v[126:127], v[126:127], v[140:141] op_sel_hi:[1,0]
	v_pk_mul_f32 v[128:129], v[128:129], v[140:141] op_sel_hi:[1,0]
	v_pk_mul_f32 v[122:123], v[122:123], v[140:141] op_sel_hi:[1,0]
	v_pk_mul_f32 v[124:125], v[124:125], v[140:141] op_sel_hi:[1,0]
	v_pk_mul_f32 v[136:137], v[88:89], v[136:137]
	v_pk_mul_f32 v[134:135], v[86:87], v[134:135]
	v_pk_mul_f32 v[132:133], v[84:85], v[132:133]
	v_pk_mul_f32 v[130:131], v[82:83], v[130:131]
	v_pk_mul_f32 v[128:129], v[96:97], v[128:129]
	v_pk_mul_f32 v[126:127], v[94:95], v[126:127]
	v_pk_mul_f32 v[124:125], v[92:93], v[124:125]
	v_pk_mul_f32 v[122:123], v[90:91], v[122:123]
	s_and_b64 vcc, exec, s[14:15]
	s_cbranch_vccz .LBB0_2960

.LBB0_2933:
	v_mov_b32_e32 v140, v182
	v_mov_b32_e32 v141, v182
	v_pk_mul_f32 v[134:135], v[182:183], v[134:135]
	v_pk_mul_f32 v[142:143], v[140:141], v[132:133]
	v_pk_mul_f32 v[132:133], v[182:183], v[130:131]
	v_cvt_pk_bf16_f32 v130, v134, v135
	v_mov_b64_e32 v[134:135], s[22:23]
	v_mad_i64_i32 v[134:135], s[2:3], v138, s72, v[134:135]
	v_lshl_add_u64 v[134:135], s[0:1], 1, v[134:135]
	v_pk_mul_f32 v[136:137], v[140:141], v[136:137]
	v_lshl_add_u64 v[134:135], v[134:135], 0, v[162:163]
	v_cvt_pk_bf16_f32 v131, v136, v137
	v_cvt_pk_bf16_f32 v132, v132, v133
	v_cvt_pk_bf16_f32 v133, v142, v143
	global_store_dwordx4 v[134:135], v[130:133], off
	v_pk_mul_f32 v[128:129], v[140:141], v[128:129]
	v_pk_mul_f32 v[126:127], v[182:183], v[126:127]
	v_pk_mul_f32 v[130:131], v[140:141], v[124:125]
	v_pk_mul_f32 v[124:125], v[182:183], v[122:123]
	v_cvt_pk_bf16_f32 v122, v126, v127
	v_cvt_pk_bf16_f32 v123, v128, v129
	s_nop 0
	v_cvt_pk_bf16_f32 v124, v124, v125
	v_cvt_pk_bf16_f32 v125, v130, v131
	v_or_b32_e32 v130, 48, v180
	v_ashrrev_i32_e32 v131, 31, v130
	global_store_dwordx4 v[134:135], v[122:125], off offset:64
	s_nop 1
	v_lshlrev_b64 v[122:123], 6, v[130:131]
	v_lshl_add_u64 v[136:137], s[36:37], 0, v[122:123]
	global_load_dwordx4 v[122:125], v[136:137], off
	global_load_dwordx4 v[126:129], v[136:137], off offset:16
	global_load_dwordx4 v[132:135], v[136:137], off offset:32
	s_nop 0
	global_load_dwordx4 v[136:139], v[136:137], off offset:48
	s_waitcnt vmcnt(3)
	v_mov_b32_e32 v140, v123
	v_mov_b32_e32 v141, v124
	v_mov_b32_e32 v123, v125
	s_waitcnt vmcnt(2)
	v_mov_b32_e32 v124, v127
	v_mov_b32_e32 v125, v128
	v_mov_b32_e32 v127, v129
	v_pk_add_f32 v[122:123], v[140:141], v[122:123]
	v_pk_add_f32 v[124:125], v[124:125], v[126:127]
	v_pk_add_f32 v[122:123], v[122:123], v[122:123] op_sel:[0,1] op_sel_hi:[1,0]
	v_pk_add_f32 v[124:125], v[124:125], v[124:125] op_sel:[0,1] op_sel_hi:[1,0]
	s_waitcnt vmcnt(1)
	v_add_f32_e32 v128, v132, v133
	v_add_f32_e32 v132, v134, v135
	s_waitcnt vmcnt(0)
	v_mov_b32_e32 v129, v138
	v_mov_b32_e32 v133, v139
	v_mov_b32_e32 v123, v136
	v_mov_b32_e32 v125, v137
	v_pk_add_f32 v[126:127], v[128:129], v[132:133]
	v_pk_add_f32 v[122:123], v[122:123], v[124:125]
	s_nop 0
	v_pk_add_f32 v[122:123], v[122:123], v[126:127]
	s_nop 0
	v_add_f32_e32 v122, v122, v123
	v_fmamk_f32 v122, v122, 0x3a800000, v186
	v_mul_f32_e32 v123, 0x4f800000, v122
	v_cmp_gt_f32_e32 vcc, s70, v122
	s_nop 1
	v_cndmask_b32_e32 v122, v122, v123, vcc
	v_sqrt_f32_e32 v123, v122
	s_nop 0
	v_add_u32_e32 v124, -1, v123
	v_add_u32_e32 v125, 1, v123
	v_fma_f32 v126, -v124, v123, v122
	v_fma_f32 v127, -v125, v123, v122
	v_cmp_ge_f32_e64 s[16:17], 0, v126
	s_nop 1
	v_cndmask_b32_e64 v123, v123, v124, s[16:17]
	v_cmp_lt_f32_e64 s[16:17], 0, v127
	s_nop 1
	v_cndmask_b32_e64 v123, v123, v125, s[16:17]
	v_mul_f32_e32 v124, 0x37800000, v123
	v_cndmask_b32_e32 v123, v123, v124, vcc
	v_cmp_class_f32_e32 vcc, v122, v187
	s_nop 1
	v_cndmask_b32_e32 v122, v123, v122, vcc
	v_div_scale_f32 v123, s[2:3], v122, v122, 1.0
	v_rcp_f32_e32 v124, v123
	v_div_scale_f32 v125, vcc, 1.0, v122, 1.0
	v_fma_f32 v126, -v123, v124, 1.0
	v_fmac_f32_e32 v124, v126, v124
	v_mul_f32_e32 v126, v125, v124
	v_fma_f32 v127, -v123, v126, v125
	v_fmac_f32_e32 v126, v127, v124
	v_fma_f32 v123, -v123, v126, v125
	v_div_fmas_f32 v123, v123, v124, v126
	v_div_fixup_f32 v132, v123, v122, 1.0
	s_and_b64 vcc, exec, s[10:11]
	v_pk_mul_f32 v[128:129], v[40:41], v[132:133] op_sel_hi:[1,0]
	v_pk_mul_f32 v[126:127], v[38:39], v[132:133] op_sel_hi:[1,0]
	v_pk_mul_f32 v[124:125], v[36:37], v[132:133] op_sel_hi:[1,0]
	v_pk_mul_f32 v[122:123], v[34:35], v[132:133] op_sel_hi:[1,0]
	v_pk_mul_f32 v[120:121], v[120:121], v[132:133] op_sel_hi:[1,0]
	v_pk_mul_f32 v[118:119], v[118:119], v[132:133] op_sel_hi:[1,0]
	v_pk_mul_f32 v[116:117], v[116:117], v[132:133] op_sel_hi:[1,0]
	v_pk_mul_f32 v[114:115], v[114:115], v[132:133] op_sel_hi:[1,0]
	s_cbranch_vccnz .LBB0_2961
	v_pk_mul_f32 v[132:133], v[128:129], v[128:129]
	v_pk_mul_f32 v[134:135], v[126:127], v[126:127]
	s_nop 0
	v_pk_mov_b32 v[136:137], v[134:135], v[132:133] op_sel:[1,0]
	v_mov_b32_e32 v135, v133
	v_pk_add_f32 v[132:133], v[136:137], v[134:135]
	v_pk_mul_f32 v[134:135], v[124:125], v[124:125]
	v_pk_add_f32 v[132:133], v[132:133], v[132:133] op_sel_hi:[0,1]
	v_pk_mul_f32 v[136:137], v[122:123], v[122:123]
	v_mul_f32_e32 v132, v118, v118
	v_pk_mov_b32 v[138:139], v[136:137], v[134:135] op_sel:[1,0]
	v_mov_b32_e32 v137, v135
	v_pk_add_f32 v[134:135], v[138:139], v[136:137]
	v_pk_fma_f32 v[136:137], v[118:119], v[118:119], v[132:133] op_sel_hi:[1,1,0]
	v_mul_f32_e32 v132, v120, v120
	v_pk_add_f32 v[134:135], v[134:135], v[134:135] op_sel_hi:[0,1]
	v_pk_fma_f32 v[138:139], v[120:121], v[120:121], v[132:133] op_sel_hi:[1,1,0]
	v_mul_f32_e32 v136, v114, v114
	v_mul_f32_e32 v138, v115, v115
	v_mul_f32_e32 v132, v116, v116
	v_mul_f32_e32 v134, v117, v117
	v_pk_add_f32 v[136:137], v[136:137], v[138:139]
	v_pk_add_f32 v[132:133], v[132:133], v[134:135]
	s_nop 0
	v_pk_add_f32 v[132:133], v[136:137], v[132:133]
	s_nop 0
	v_add_f32_e32 v131, v132, v133
	v_and_b32_e32 v133, 64, v191
	v_xor_b32_e32 v132, 16, v191
	v_add_u32_e32 v133, 64, v133
	v_cmp_lt_i32_e32 vcc, v132, v133
	s_nop 1
	v_cndmask_b32_e32 v132, v191, v132, vcc
	v_lshlrev_b32_e32 v132, 2, v132
	ds_bpermute_b32 v132, v132, v131
	s_waitcnt lgkmcnt(0)
	v_add_f32_e32 v131, v131, v132
	v_xor_b32_e32 v132, 32, v191
	v_cmp_lt_i32_e32 vcc, v132, v133
	s_nop 1
	v_cndmask_b32_e32 v132, v191, v132, vcc
	v_lshlrev_b32_e32 v132, 2, v132
	ds_bpermute_b32 v132, v132, v131
	s_waitcnt lgkmcnt(0)
	v_add_f32_e32 v131, v131, v132
	v_fmamk_f32 v131, v131, 0x3c800000, v186
	v_mul_f32_e32 v132, 0x4f800000, v131
	v_cmp_gt_f32_e32 vcc, s70, v131
	s_nop 1
	v_cndmask_b32_e32 v131, v131, v132, vcc
	v_sqrt_f32_e32 v132, v131
	s_nop 0
	v_add_u32_e32 v133, -1, v132
	v_fma_f32 v134, -v133, v132, v131
	v_cmp_ge_f32_e64 s[16:17], 0, v134
	v_add_u32_e32 v134, 1, v132
	s_nop 0
	v_cndmask_b32_e64 v133, v132, v133, s[16:17]
	v_fma_f32 v132, -v134, v132, v131
	v_cmp_lt_f32_e64 s[16:17], 0, v132
	s_nop 1
	v_cndmask_b32_e64 v132, v133, v134, s[16:17]
	v_mul_f32_e32 v133, 0x37800000, v132
	v_cndmask_b32_e32 v132, v132, v133, vcc
	v_cmp_class_f32_e32 vcc, v131, v187
	s_nop 1
	v_cndmask_b32_e32 v131, v132, v131, vcc
	v_div_scale_f32 v132, s[2:3], v131, v131, 1.0
	v_rcp_f32_e32 v133, v132
	s_nop 0
	v_fma_f32 v134, -v132, v133, 1.0
	v_fmac_f32_e32 v133, v134, v133
	v_div_scale_f32 v134, vcc, 1.0, v131, 1.0
	v_mul_f32_e32 v135, v134, v133
	v_fma_f32 v136, -v132, v135, v134
	v_fmac_f32_e32 v135, v136, v133
	v_fma_f32 v132, -v132, v135, v134
	v_div_fmas_f32 v132, v132, v133, v135
	v_div_fixup_f32 v132, v132, v131, 1.0
	v_pk_mul_f32 v[126:127], v[126:127], v[132:133] op_sel_hi:[1,0]
	v_pk_mul_f32 v[128:129], v[128:129], v[132:133] op_sel_hi:[1,0]
	v_pk_mul_f32 v[122:123], v[122:123], v[132:133] op_sel_hi:[1,0]
	v_pk_mul_f32 v[124:125], v[124:125], v[132:133] op_sel_hi:[1,0]
	v_pk_mul_f32 v[118:119], v[118:119], v[132:133] op_sel_hi:[1,0]
	v_pk_mul_f32 v[120:121], v[120:121], v[132:133] op_sel_hi:[1,0]
	v_pk_mul_f32 v[114:115], v[114:115], v[132:133] op_sel_hi:[1,0]
	v_pk_mul_f32 v[116:117], v[116:117], v[132:133] op_sel_hi:[1,0]
	v_pk_mul_f32 v[128:129], v[88:89], v[128:129]
	v_pk_mul_f32 v[126:127], v[86:87], v[126:127]
	v_pk_mul_f32 v[124:125], v[84:85], v[124:125]
	v_pk_mul_f32 v[122:123], v[82:83], v[122:123]
	v_pk_mul_f32 v[120:121], v[96:97], v[120:121]
	v_pk_mul_f32 v[118:119], v[94:95], v[118:119]
	v_pk_mul_f32 v[116:117], v[92:93], v[116:117]
	v_pk_mul_f32 v[114:115], v[90:91], v[114:115]
	s_and_b64 vcc, exec, s[14:15]
	s_cbranch_vccz .LBB0_2962

.LBB0_2937:
	v_mov_b32_e32 v132, v182
	v_mov_b32_e32 v133, v182
	v_pk_mul_f32 v[126:127], v[182:183], v[126:127]
	v_pk_mul_f32 v[134:135], v[132:133], v[124:125]
	v_pk_mul_f32 v[124:125], v[182:183], v[122:123]
	v_cvt_pk_bf16_f32 v122, v126, v127
	v_mov_b64_e32 v[126:127], s[22:23]
	v_mad_i64_i32 v[126:127], s[2:3], v130, s72, v[126:127]
	v_lshl_add_u64 v[126:127], s[0:1], 1, v[126:127]
	v_pk_mul_f32 v[128:129], v[132:133], v[128:129]
	v_lshl_add_u64 v[126:127], v[126:127], 0, v[162:163]
	v_cvt_pk_bf16_f32 v123, v128, v129
	v_cvt_pk_bf16_f32 v124, v124, v125
	v_cvt_pk_bf16_f32 v125, v134, v135
	global_store_dwordx4 v[126:127], v[122:125], off
	v_pk_mul_f32 v[120:121], v[132:133], v[120:121]
	v_pk_mul_f32 v[118:119], v[182:183], v[118:119]
	v_pk_mul_f32 v[122:123], v[132:133], v[116:117]
	v_pk_mul_f32 v[116:117], v[182:183], v[114:115]
	v_cvt_pk_bf16_f32 v114, v118, v119
	v_cvt_pk_bf16_f32 v115, v120, v121
	s_nop 0
	v_cvt_pk_bf16_f32 v116, v116, v117
	v_cvt_pk_bf16_f32 v117, v122, v123
	v_add_u32_e32 v122, 0x80, v180
	v_ashrrev_i32_e32 v123, 31, v122
	global_store_dwordx4 v[126:127], v[114:117], off offset:64
	s_nop 1
	v_lshlrev_b64 v[114:115], 6, v[122:123]
	v_lshl_add_u64 v[128:129], s[36:37], 0, v[114:115]
	global_load_dwordx4 v[114:117], v[128:129], off
	global_load_dwordx4 v[118:121], v[128:129], off offset:16
	global_load_dwordx4 v[124:127], v[128:129], off offset:32
	s_nop 0
	global_load_dwordx4 v[128:131], v[128:129], off offset:48
	s_waitcnt vmcnt(3)
	v_mov_b32_e32 v132, v115
	v_mov_b32_e32 v133, v116
	v_mov_b32_e32 v115, v117
	s_waitcnt vmcnt(2)
	v_mov_b32_e32 v116, v119
	v_mov_b32_e32 v117, v120
	v_mov_b32_e32 v119, v121
	v_pk_add_f32 v[114:115], v[132:133], v[114:115]
	v_pk_add_f32 v[116:117], v[116:117], v[118:119]
	v_pk_add_f32 v[114:115], v[114:115], v[114:115] op_sel:[0,1] op_sel_hi:[1,0]
	v_pk_add_f32 v[116:117], v[116:117], v[116:117] op_sel:[0,1] op_sel_hi:[1,0]
	s_waitcnt vmcnt(1)
	v_add_f32_e32 v120, v124, v125
	v_add_f32_e32 v124, v126, v127
	s_waitcnt vmcnt(0)
	v_mov_b32_e32 v121, v130
	v_mov_b32_e32 v125, v131
	v_mov_b32_e32 v115, v128
	v_mov_b32_e32 v117, v129
	v_pk_add_f32 v[118:119], v[120:121], v[124:125]
	v_pk_add_f32 v[114:115], v[114:115], v[116:117]
	s_nop 0
	v_pk_add_f32 v[114:115], v[114:115], v[118:119]
	s_nop 0
	v_add_f32_e32 v114, v114, v115
	v_fmamk_f32 v114, v114, 0x3a800000, v186
	v_mul_f32_e32 v115, 0x4f800000, v114
	v_cmp_gt_f32_e32 vcc, s70, v114
	s_nop 1
	v_cndmask_b32_e32 v114, v114, v115, vcc
	v_sqrt_f32_e32 v115, v114
	s_nop 0
	v_add_u32_e32 v116, -1, v115
	v_add_u32_e32 v117, 1, v115
	v_fma_f32 v118, -v116, v115, v114
	v_fma_f32 v119, -v117, v115, v114
	v_cmp_ge_f32_e64 s[16:17], 0, v118
	s_nop 1
	v_cndmask_b32_e64 v115, v115, v116, s[16:17]
	v_cmp_lt_f32_e64 s[16:17], 0, v119
	s_nop 1
	v_cndmask_b32_e64 v115, v115, v117, s[16:17]
	v_mul_f32_e32 v116, 0x37800000, v115
	v_cndmask_b32_e32 v115, v115, v116, vcc
	v_cmp_class_f32_e32 vcc, v114, v187
	s_nop 1
	v_cndmask_b32_e32 v114, v115, v114, vcc
	v_div_scale_f32 v115, s[2:3], v114, v114, 1.0
	v_rcp_f32_e32 v116, v115
	v_div_scale_f32 v117, vcc, 1.0, v114, 1.0
	v_fma_f32 v118, -v115, v116, 1.0
	v_fmac_f32_e32 v116, v118, v116
	v_mul_f32_e32 v118, v117, v116
	v_fma_f32 v119, -v115, v118, v117
	v_fmac_f32_e32 v118, v119, v116
	v_fma_f32 v115, -v115, v118, v117
	v_div_fmas_f32 v115, v115, v116, v118
	v_div_fixup_f32 v124, v115, v114, 1.0
	s_and_b64 vcc, exec, s[10:11]
	v_pk_mul_f32 v[120:121], v[32:33], v[124:125] op_sel_hi:[1,0]
	v_pk_mul_f32 v[118:119], v[30:31], v[124:125] op_sel_hi:[1,0]
	v_pk_mul_f32 v[116:117], v[28:29], v[124:125] op_sel_hi:[1,0]
	v_pk_mul_f32 v[114:115], v[26:27], v[124:125] op_sel_hi:[1,0]
	v_pk_mul_f32 v[112:113], v[112:113], v[124:125] op_sel_hi:[1,0]
	v_pk_mul_f32 v[110:111], v[110:111], v[124:125] op_sel_hi:[1,0]
	v_pk_mul_f32 v[108:109], v[108:109], v[124:125] op_sel_hi:[1,0]
	v_pk_mul_f32 v[106:107], v[106:107], v[124:125] op_sel_hi:[1,0]
	s_cbranch_vccnz .LBB0_2963
	v_pk_mul_f32 v[124:125], v[120:121], v[120:121]
	v_pk_mul_f32 v[126:127], v[118:119], v[118:119]
	s_nop 0
	v_pk_mov_b32 v[128:129], v[126:127], v[124:125] op_sel:[1,0]
	v_mov_b32_e32 v127, v125
	v_pk_add_f32 v[124:125], v[128:129], v[126:127]
	v_pk_mul_f32 v[126:127], v[116:117], v[116:117]
	v_pk_add_f32 v[124:125], v[124:125], v[124:125] op_sel_hi:[0,1]
	v_pk_mul_f32 v[128:129], v[114:115], v[114:115]
	v_mul_f32_e32 v124, v110, v110
	v_pk_mov_b32 v[130:131], v[128:129], v[126:127] op_sel:[1,0]
	v_mov_b32_e32 v129, v127
	v_pk_add_f32 v[126:127], v[130:131], v[128:129]
	v_pk_fma_f32 v[128:129], v[110:111], v[110:111], v[124:125] op_sel_hi:[1,1,0]
	v_mul_f32_e32 v124, v112, v112
	v_pk_add_f32 v[126:127], v[126:127], v[126:127] op_sel_hi:[0,1]
	v_pk_fma_f32 v[130:131], v[112:113], v[112:113], v[124:125] op_sel_hi:[1,1,0]
	v_mul_f32_e32 v128, v106, v106
	v_mul_f32_e32 v130, v107, v107
	v_mul_f32_e32 v124, v108, v108
	v_mul_f32_e32 v126, v109, v109
	v_pk_add_f32 v[128:129], v[128:129], v[130:131]
	v_pk_add_f32 v[124:125], v[124:125], v[126:127]
	s_nop 0
	v_pk_add_f32 v[124:125], v[128:129], v[124:125]
	s_nop 0
	v_add_f32_e32 v123, v124, v125
	v_and_b32_e32 v125, 64, v191
	v_xor_b32_e32 v124, 16, v191
	v_add_u32_e32 v125, 64, v125
	v_cmp_lt_i32_e32 vcc, v124, v125
	s_nop 1
	v_cndmask_b32_e32 v124, v191, v124, vcc
	v_lshlrev_b32_e32 v124, 2, v124
	ds_bpermute_b32 v124, v124, v123
	s_waitcnt lgkmcnt(0)
	v_add_f32_e32 v123, v123, v124
	v_xor_b32_e32 v124, 32, v191
	v_cmp_lt_i32_e32 vcc, v124, v125
	s_nop 1
	v_cndmask_b32_e32 v124, v191, v124, vcc
	v_lshlrev_b32_e32 v124, 2, v124
	ds_bpermute_b32 v124, v124, v123
	s_waitcnt lgkmcnt(0)
	v_add_f32_e32 v123, v123, v124
	v_fmamk_f32 v123, v123, 0x3c800000, v186
	v_mul_f32_e32 v124, 0x4f800000, v123
	v_cmp_gt_f32_e32 vcc, s70, v123
	s_nop 1
	v_cndmask_b32_e32 v123, v123, v124, vcc
	v_sqrt_f32_e32 v124, v123
	s_nop 0
	v_add_u32_e32 v125, -1, v124
	v_fma_f32 v126, -v125, v124, v123
	v_cmp_ge_f32_e64 s[16:17], 0, v126
	v_add_u32_e32 v126, 1, v124
	s_nop 0
	v_cndmask_b32_e64 v125, v124, v125, s[16:17]
	v_fma_f32 v124, -v126, v124, v123
	v_cmp_lt_f32_e64 s[16:17], 0, v124
	s_nop 1
	v_cndmask_b32_e64 v124, v125, v126, s[16:17]
	v_mul_f32_e32 v125, 0x37800000, v124
	v_cndmask_b32_e32 v124, v124, v125, vcc
	v_cmp_class_f32_e32 vcc, v123, v187
	s_nop 1
	v_cndmask_b32_e32 v123, v124, v123, vcc
	v_div_scale_f32 v124, s[2:3], v123, v123, 1.0
	v_rcp_f32_e32 v125, v124
	s_nop 0
	v_fma_f32 v126, -v124, v125, 1.0
	v_fmac_f32_e32 v125, v126, v125
	v_div_scale_f32 v126, vcc, 1.0, v123, 1.0
	v_mul_f32_e32 v127, v126, v125
	v_fma_f32 v128, -v124, v127, v126
	v_fmac_f32_e32 v127, v128, v125
	v_fma_f32 v124, -v124, v127, v126
	v_div_fmas_f32 v124, v124, v125, v127
	v_div_fixup_f32 v124, v124, v123, 1.0
	v_pk_mul_f32 v[118:119], v[118:119], v[124:125] op_sel_hi:[1,0]
	v_pk_mul_f32 v[120:121], v[120:121], v[124:125] op_sel_hi:[1,0]
	v_pk_mul_f32 v[114:115], v[114:115], v[124:125] op_sel_hi:[1,0]
	v_pk_mul_f32 v[116:117], v[116:117], v[124:125] op_sel_hi:[1,0]
	v_pk_mul_f32 v[110:111], v[110:111], v[124:125] op_sel_hi:[1,0]
	v_pk_mul_f32 v[112:113], v[112:113], v[124:125] op_sel_hi:[1,0]
	v_pk_mul_f32 v[106:107], v[106:107], v[124:125] op_sel_hi:[1,0]
	v_pk_mul_f32 v[108:109], v[108:109], v[124:125] op_sel_hi:[1,0]
	v_pk_mul_f32 v[120:121], v[88:89], v[120:121]
	v_pk_mul_f32 v[118:119], v[86:87], v[118:119]
	v_pk_mul_f32 v[116:117], v[84:85], v[116:117]
	v_pk_mul_f32 v[114:115], v[82:83], v[114:115]
	v_pk_mul_f32 v[112:113], v[96:97], v[112:113]
	v_pk_mul_f32 v[110:111], v[94:95], v[110:111]
	v_pk_mul_f32 v[108:109], v[92:93], v[108:109]
	v_pk_mul_f32 v[106:107], v[90:91], v[106:107]
	s_and_b64 vcc, exec, s[14:15]
	s_cbranch_vccz .LBB0_2964

.LBB0_2941:
	v_mov_b32_e32 v124, v182
	v_mov_b32_e32 v125, v182
	v_pk_mul_f32 v[118:119], v[182:183], v[118:119]
	v_pk_mul_f32 v[126:127], v[124:125], v[116:117]
	v_pk_mul_f32 v[116:117], v[182:183], v[114:115]
	v_cvt_pk_bf16_f32 v114, v118, v119
	v_mov_b64_e32 v[118:119], s[22:23]
	v_mad_i64_i32 v[118:119], s[2:3], v122, s72, v[118:119]
	v_lshl_add_u64 v[118:119], s[0:1], 1, v[118:119]
	v_pk_mul_f32 v[120:121], v[124:125], v[120:121]
	v_lshl_add_u64 v[118:119], v[118:119], 0, v[162:163]
	v_cvt_pk_bf16_f32 v115, v120, v121
	v_cvt_pk_bf16_f32 v116, v116, v117
	v_cvt_pk_bf16_f32 v117, v126, v127
	global_store_dwordx4 v[118:119], v[114:117], off
	v_pk_mul_f32 v[112:113], v[124:125], v[112:113]
	v_pk_mul_f32 v[110:111], v[182:183], v[110:111]
	v_pk_mul_f32 v[114:115], v[124:125], v[108:109]
	v_pk_mul_f32 v[108:109], v[182:183], v[106:107]
	v_cvt_pk_bf16_f32 v106, v110, v111
	v_cvt_pk_bf16_f32 v107, v112, v113
	s_nop 0
	v_cvt_pk_bf16_f32 v108, v108, v109
	v_cvt_pk_bf16_f32 v109, v114, v115
	v_add_u32_e32 v114, 0x90, v180
	v_ashrrev_i32_e32 v115, 31, v114
	global_store_dwordx4 v[118:119], v[106:109], off offset:64
	s_nop 1
	v_lshlrev_b64 v[106:107], 6, v[114:115]
	v_lshl_add_u64 v[120:121], s[36:37], 0, v[106:107]
	global_load_dwordx4 v[106:109], v[120:121], off
	global_load_dwordx4 v[110:113], v[120:121], off offset:16
	global_load_dwordx4 v[116:119], v[120:121], off offset:32
	s_nop 0
	global_load_dwordx4 v[120:123], v[120:121], off offset:48
	s_waitcnt vmcnt(3)
	v_mov_b32_e32 v124, v107
	v_mov_b32_e32 v125, v108
	v_mov_b32_e32 v107, v109
	s_waitcnt vmcnt(2)
	v_mov_b32_e32 v108, v111
	v_mov_b32_e32 v109, v112
	v_mov_b32_e32 v111, v113
	v_pk_add_f32 v[106:107], v[124:125], v[106:107]
	v_pk_add_f32 v[108:109], v[108:109], v[110:111]
	v_pk_add_f32 v[106:107], v[106:107], v[106:107] op_sel:[0,1] op_sel_hi:[1,0]
	v_pk_add_f32 v[108:109], v[108:109], v[108:109] op_sel:[0,1] op_sel_hi:[1,0]
	s_waitcnt vmcnt(1)
	v_add_f32_e32 v112, v116, v117
	v_add_f32_e32 v116, v118, v119
	s_waitcnt vmcnt(0)
	v_mov_b32_e32 v113, v122
	v_mov_b32_e32 v117, v123
	v_mov_b32_e32 v107, v120
	v_mov_b32_e32 v109, v121
	v_pk_add_f32 v[110:111], v[112:113], v[116:117]
	v_pk_add_f32 v[106:107], v[106:107], v[108:109]
	s_nop 0
	v_pk_add_f32 v[106:107], v[106:107], v[110:111]
	s_nop 0
	v_add_f32_e32 v106, v106, v107
	v_fmamk_f32 v106, v106, 0x3a800000, v186
	v_mul_f32_e32 v107, 0x4f800000, v106
	v_cmp_gt_f32_e32 vcc, s70, v106
	s_nop 1
	v_cndmask_b32_e32 v106, v106, v107, vcc
	v_sqrt_f32_e32 v107, v106
	s_nop 0
	v_add_u32_e32 v108, -1, v107
	v_add_u32_e32 v109, 1, v107
	v_fma_f32 v110, -v108, v107, v106
	v_fma_f32 v111, -v109, v107, v106
	v_cmp_ge_f32_e64 s[16:17], 0, v110
	s_nop 1
	v_cndmask_b32_e64 v107, v107, v108, s[16:17]
	v_cmp_lt_f32_e64 s[16:17], 0, v111
	s_nop 1
	v_cndmask_b32_e64 v107, v107, v109, s[16:17]
	v_mul_f32_e32 v108, 0x37800000, v107
	v_cndmask_b32_e32 v107, v107, v108, vcc
	v_cmp_class_f32_e32 vcc, v106, v187
	s_nop 1
	v_cndmask_b32_e32 v106, v107, v106, vcc
	v_div_scale_f32 v107, s[2:3], v106, v106, 1.0
	v_rcp_f32_e32 v108, v107
	v_div_scale_f32 v109, vcc, 1.0, v106, 1.0
	v_fma_f32 v110, -v107, v108, 1.0
	v_fmac_f32_e32 v108, v110, v108
	v_mul_f32_e32 v110, v109, v108
	v_fma_f32 v111, -v107, v110, v109
	v_fmac_f32_e32 v110, v111, v108
	v_fma_f32 v107, -v107, v110, v109
	v_div_fmas_f32 v107, v107, v108, v110
	v_div_fixup_f32 v116, v107, v106, 1.0
	s_and_b64 vcc, exec, s[10:11]
	v_pk_mul_f32 v[112:113], v[24:25], v[116:117] op_sel_hi:[1,0]
	v_pk_mul_f32 v[110:111], v[22:23], v[116:117] op_sel_hi:[1,0]
	v_pk_mul_f32 v[108:109], v[20:21], v[116:117] op_sel_hi:[1,0]
	v_pk_mul_f32 v[106:107], v[18:19], v[116:117] op_sel_hi:[1,0]
	v_pk_mul_f32 v[104:105], v[104:105], v[116:117] op_sel_hi:[1,0]
	v_pk_mul_f32 v[102:103], v[102:103], v[116:117] op_sel_hi:[1,0]
	v_pk_mul_f32 v[100:101], v[100:101], v[116:117] op_sel_hi:[1,0]
	v_pk_mul_f32 v[98:99], v[98:99], v[116:117] op_sel_hi:[1,0]
	s_cbranch_vccnz .LBB0_2965
	v_pk_mul_f32 v[116:117], v[112:113], v[112:113]
	v_pk_mul_f32 v[118:119], v[110:111], v[110:111]
	s_nop 0
	v_pk_mov_b32 v[120:121], v[118:119], v[116:117] op_sel:[1,0]
	v_mov_b32_e32 v119, v117
	v_pk_add_f32 v[116:117], v[120:121], v[118:119]
	v_pk_mul_f32 v[118:119], v[108:109], v[108:109]
	v_pk_add_f32 v[116:117], v[116:117], v[116:117] op_sel_hi:[0,1]
	v_pk_mul_f32 v[120:121], v[106:107], v[106:107]
	v_mul_f32_e32 v116, v102, v102
	v_pk_mov_b32 v[122:123], v[120:121], v[118:119] op_sel:[1,0]
	v_mov_b32_e32 v121, v119
	v_pk_add_f32 v[118:119], v[122:123], v[120:121]
	v_pk_fma_f32 v[120:121], v[102:103], v[102:103], v[116:117] op_sel_hi:[1,1,0]
	v_mul_f32_e32 v116, v104, v104
	v_pk_add_f32 v[118:119], v[118:119], v[118:119] op_sel_hi:[0,1]
	v_pk_fma_f32 v[122:123], v[104:105], v[104:105], v[116:117] op_sel_hi:[1,1,0]
	v_mul_f32_e32 v120, v98, v98
	v_mul_f32_e32 v122, v99, v99
	v_mul_f32_e32 v116, v100, v100
	v_mul_f32_e32 v118, v101, v101
	v_pk_add_f32 v[120:121], v[120:121], v[122:123]
	v_pk_add_f32 v[116:117], v[116:117], v[118:119]
	s_nop 0
	v_pk_add_f32 v[116:117], v[120:121], v[116:117]
	s_nop 0
	v_add_f32_e32 v115, v116, v117
	v_and_b32_e32 v117, 64, v191
	v_xor_b32_e32 v116, 16, v191
	v_add_u32_e32 v117, 64, v117
	v_cmp_lt_i32_e32 vcc, v116, v117
	s_nop 1
	v_cndmask_b32_e32 v116, v191, v116, vcc
	v_lshlrev_b32_e32 v116, 2, v116
	ds_bpermute_b32 v116, v116, v115
	s_waitcnt lgkmcnt(0)
	v_add_f32_e32 v115, v115, v116
	v_xor_b32_e32 v116, 32, v191
	v_cmp_lt_i32_e32 vcc, v116, v117
	s_nop 1
	v_cndmask_b32_e32 v116, v191, v116, vcc
	v_lshlrev_b32_e32 v116, 2, v116
	ds_bpermute_b32 v116, v116, v115
	s_waitcnt lgkmcnt(0)
	v_add_f32_e32 v115, v115, v116
	v_fmamk_f32 v115, v115, 0x3c800000, v186
	v_mul_f32_e32 v116, 0x4f800000, v115
	v_cmp_gt_f32_e32 vcc, s70, v115
	s_nop 1
	v_cndmask_b32_e32 v115, v115, v116, vcc
	v_sqrt_f32_e32 v116, v115
	s_nop 0
	v_add_u32_e32 v117, -1, v116
	v_fma_f32 v118, -v117, v116, v115
	v_cmp_ge_f32_e64 s[16:17], 0, v118
	v_add_u32_e32 v118, 1, v116
	s_nop 0
	v_cndmask_b32_e64 v117, v116, v117, s[16:17]
	v_fma_f32 v116, -v118, v116, v115
	v_cmp_lt_f32_e64 s[16:17], 0, v116
	s_nop 1
	v_cndmask_b32_e64 v116, v117, v118, s[16:17]
	v_mul_f32_e32 v117, 0x37800000, v116
	v_cndmask_b32_e32 v116, v116, v117, vcc
	v_cmp_class_f32_e32 vcc, v115, v187
	s_nop 1
	v_cndmask_b32_e32 v115, v116, v115, vcc
	v_div_scale_f32 v116, s[2:3], v115, v115, 1.0
	v_rcp_f32_e32 v117, v116
	s_nop 0
	v_fma_f32 v118, -v116, v117, 1.0
	v_fmac_f32_e32 v117, v118, v117
	v_div_scale_f32 v118, vcc, 1.0, v115, 1.0
	v_mul_f32_e32 v119, v118, v117
	v_fma_f32 v120, -v116, v119, v118
	v_fmac_f32_e32 v119, v120, v117
	v_fma_f32 v116, -v116, v119, v118
	v_div_fmas_f32 v116, v116, v117, v119
	v_div_fixup_f32 v116, v116, v115, 1.0
	v_pk_mul_f32 v[110:111], v[110:111], v[116:117] op_sel_hi:[1,0]
	v_pk_mul_f32 v[112:113], v[112:113], v[116:117] op_sel_hi:[1,0]
	v_pk_mul_f32 v[106:107], v[106:107], v[116:117] op_sel_hi:[1,0]
	v_pk_mul_f32 v[108:109], v[108:109], v[116:117] op_sel_hi:[1,0]
	v_pk_mul_f32 v[102:103], v[102:103], v[116:117] op_sel_hi:[1,0]
	v_pk_mul_f32 v[104:105], v[104:105], v[116:117] op_sel_hi:[1,0]
	v_pk_mul_f32 v[98:99], v[98:99], v[116:117] op_sel_hi:[1,0]
	v_pk_mul_f32 v[100:101], v[100:101], v[116:117] op_sel_hi:[1,0]
	v_pk_mul_f32 v[112:113], v[88:89], v[112:113]
	v_pk_mul_f32 v[110:111], v[86:87], v[110:111]
	v_pk_mul_f32 v[108:109], v[84:85], v[108:109]
	v_pk_mul_f32 v[106:107], v[82:83], v[106:107]
	v_pk_mul_f32 v[104:105], v[96:97], v[104:105]
	v_pk_mul_f32 v[102:103], v[94:95], v[102:103]
	v_pk_mul_f32 v[100:101], v[92:93], v[100:101]
	v_pk_mul_f32 v[98:99], v[90:91], v[98:99]
	s_and_b64 vcc, exec, s[14:15]
	s_cbranch_vccz .LBB0_2966

.LBB0_2945:
	v_mov_b32_e32 v116, v182
	v_mov_b32_e32 v117, v182
	v_pk_mul_f32 v[110:111], v[182:183], v[110:111]
	v_pk_mul_f32 v[118:119], v[116:117], v[108:109]
	v_pk_mul_f32 v[108:109], v[182:183], v[106:107]
	v_cvt_pk_bf16_f32 v106, v110, v111
	v_mov_b64_e32 v[110:111], s[22:23]
	v_mad_i64_i32 v[110:111], s[2:3], v114, s72, v[110:111]
	v_lshl_add_u64 v[110:111], s[0:1], 1, v[110:111]
	v_pk_mul_f32 v[112:113], v[116:117], v[112:113]
	v_lshl_add_u64 v[110:111], v[110:111], 0, v[162:163]
	v_cvt_pk_bf16_f32 v107, v112, v113
	v_cvt_pk_bf16_f32 v108, v108, v109
	v_cvt_pk_bf16_f32 v109, v118, v119
	global_store_dwordx4 v[110:111], v[106:109], off
	v_pk_mul_f32 v[104:105], v[116:117], v[104:105]
	v_pk_mul_f32 v[102:103], v[182:183], v[102:103]
	v_pk_mul_f32 v[106:107], v[116:117], v[100:101]
	v_pk_mul_f32 v[100:101], v[182:183], v[98:99]
	v_cvt_pk_bf16_f32 v98, v102, v103
	v_cvt_pk_bf16_f32 v99, v104, v105
	s_nop 0
	v_cvt_pk_bf16_f32 v100, v100, v101
	v_cvt_pk_bf16_f32 v101, v106, v107
	v_add_u32_e32 v106, 0xa0, v180
	v_ashrrev_i32_e32 v107, 31, v106
	global_store_dwordx4 v[110:111], v[98:101], off offset:64
	s_nop 1
	v_lshlrev_b64 v[98:99], 6, v[106:107]
	v_lshl_add_u64 v[112:113], s[36:37], 0, v[98:99]
	global_load_dwordx4 v[98:101], v[112:113], off
	global_load_dwordx4 v[102:105], v[112:113], off offset:16
	global_load_dwordx4 v[108:111], v[112:113], off offset:32
	s_nop 0
	global_load_dwordx4 v[112:115], v[112:113], off offset:48
	s_waitcnt vmcnt(3)
	v_mov_b32_e32 v116, v99
	v_mov_b32_e32 v117, v100
	v_mov_b32_e32 v99, v101
	s_waitcnt vmcnt(2)
	v_mov_b32_e32 v100, v103
	v_mov_b32_e32 v101, v104
	v_mov_b32_e32 v103, v105
	v_pk_add_f32 v[98:99], v[116:117], v[98:99]
	v_pk_add_f32 v[100:101], v[100:101], v[102:103]
	v_pk_add_f32 v[98:99], v[98:99], v[98:99] op_sel:[0,1] op_sel_hi:[1,0]
	v_pk_add_f32 v[100:101], v[100:101], v[100:101] op_sel:[0,1] op_sel_hi:[1,0]
	s_waitcnt vmcnt(1)
	v_add_f32_e32 v104, v108, v109
	v_add_f32_e32 v108, v110, v111
	s_waitcnt vmcnt(0)
	v_mov_b32_e32 v105, v114
	v_mov_b32_e32 v109, v115
	v_mov_b32_e32 v99, v112
	v_mov_b32_e32 v101, v113
	v_pk_add_f32 v[102:103], v[104:105], v[108:109]
	v_pk_add_f32 v[98:99], v[98:99], v[100:101]
	s_nop 0
	v_pk_add_f32 v[98:99], v[98:99], v[102:103]
	s_nop 0
	v_add_f32_e32 v98, v98, v99
	v_fmamk_f32 v98, v98, 0x3a800000, v186
	v_mul_f32_e32 v99, 0x4f800000, v98
	v_cmp_gt_f32_e32 vcc, s70, v98
	s_nop 1
	v_cndmask_b32_e32 v98, v98, v99, vcc
	v_sqrt_f32_e32 v99, v98
	s_nop 0
	v_add_u32_e32 v100, -1, v99
	v_add_u32_e32 v101, 1, v99
	v_fma_f32 v102, -v100, v99, v98
	v_fma_f32 v103, -v101, v99, v98
	v_cmp_ge_f32_e64 s[16:17], 0, v102
	s_nop 1
	v_cndmask_b32_e64 v99, v99, v100, s[16:17]
	v_cmp_lt_f32_e64 s[16:17], 0, v103
	s_nop 1
	v_cndmask_b32_e64 v99, v99, v101, s[16:17]
	v_mul_f32_e32 v100, 0x37800000, v99
	v_cndmask_b32_e32 v99, v99, v100, vcc
	v_cmp_class_f32_e32 vcc, v98, v187
	s_nop 1
	v_cndmask_b32_e32 v98, v99, v98, vcc
	v_div_scale_f32 v99, s[2:3], v98, v98, 1.0
	v_rcp_f32_e32 v100, v99
	v_div_scale_f32 v101, vcc, 1.0, v98, 1.0
	v_fma_f32 v102, -v99, v100, 1.0
	v_fmac_f32_e32 v100, v102, v100
	v_mul_f32_e32 v102, v101, v100
	v_fma_f32 v103, -v99, v102, v101
	v_fmac_f32_e32 v102, v103, v100
	v_fma_f32 v99, -v99, v102, v101
	v_div_fmas_f32 v99, v99, v100, v102
	v_div_fixup_f32 v108, v99, v98, 1.0
	s_and_b64 vcc, exec, s[10:11]
	v_pk_mul_f32 v[104:105], v[16:17], v[108:109] op_sel_hi:[1,0]
	v_pk_mul_f32 v[102:103], v[14:15], v[108:109] op_sel_hi:[1,0]
	v_pk_mul_f32 v[100:101], v[12:13], v[108:109] op_sel_hi:[1,0]
	v_pk_mul_f32 v[98:99], v[10:11], v[108:109] op_sel_hi:[1,0]
	v_pk_mul_f32 v[80:81], v[80:81], v[108:109] op_sel_hi:[1,0]
	v_pk_mul_f32 v[78:79], v[78:79], v[108:109] op_sel_hi:[1,0]
	v_pk_mul_f32 v[76:77], v[76:77], v[108:109] op_sel_hi:[1,0]
	v_pk_mul_f32 v[74:75], v[74:75], v[108:109] op_sel_hi:[1,0]
	s_cbranch_vccnz .LBB0_2967
	v_pk_mul_f32 v[108:109], v[104:105], v[104:105]
	v_pk_mul_f32 v[110:111], v[102:103], v[102:103]
	s_nop 0
	v_pk_mov_b32 v[112:113], v[110:111], v[108:109] op_sel:[1,0]
	v_mov_b32_e32 v111, v109
	v_pk_add_f32 v[108:109], v[112:113], v[110:111]
	v_pk_mul_f32 v[110:111], v[100:101], v[100:101]
	v_pk_add_f32 v[108:109], v[108:109], v[108:109] op_sel_hi:[0,1]
	v_pk_mul_f32 v[112:113], v[98:99], v[98:99]
	v_mul_f32_e32 v108, v78, v78
	v_pk_mov_b32 v[114:115], v[112:113], v[110:111] op_sel:[1,0]
	v_mov_b32_e32 v113, v111
	v_pk_add_f32 v[110:111], v[114:115], v[112:113]
	v_pk_fma_f32 v[112:113], v[78:79], v[78:79], v[108:109] op_sel_hi:[1,1,0]
	v_mul_f32_e32 v108, v80, v80
	v_pk_add_f32 v[110:111], v[110:111], v[110:111] op_sel_hi:[0,1]
	v_pk_fma_f32 v[114:115], v[80:81], v[80:81], v[108:109] op_sel_hi:[1,1,0]
	v_mul_f32_e32 v112, v74, v74
	v_mul_f32_e32 v114, v75, v75
	v_mul_f32_e32 v108, v76, v76
	v_mul_f32_e32 v110, v77, v77
	v_pk_add_f32 v[112:113], v[112:113], v[114:115]
	v_pk_add_f32 v[108:109], v[108:109], v[110:111]
	s_nop 0
	v_pk_add_f32 v[108:109], v[112:113], v[108:109]
	s_nop 0
	v_add_f32_e32 v107, v108, v109
	v_and_b32_e32 v109, 64, v191
	v_xor_b32_e32 v108, 16, v191
	v_add_u32_e32 v109, 64, v109
	v_cmp_lt_i32_e32 vcc, v108, v109
	s_nop 1
	v_cndmask_b32_e32 v108, v191, v108, vcc
	v_lshlrev_b32_e32 v108, 2, v108
	ds_bpermute_b32 v108, v108, v107
	s_waitcnt lgkmcnt(0)
	v_add_f32_e32 v107, v107, v108
	v_xor_b32_e32 v108, 32, v191
	v_cmp_lt_i32_e32 vcc, v108, v109
	s_nop 1
	v_cndmask_b32_e32 v108, v191, v108, vcc
	v_lshlrev_b32_e32 v108, 2, v108
	ds_bpermute_b32 v108, v108, v107
	s_waitcnt lgkmcnt(0)
	v_add_f32_e32 v107, v107, v108
	v_fmamk_f32 v107, v107, 0x3c800000, v186
	v_mul_f32_e32 v108, 0x4f800000, v107
	v_cmp_gt_f32_e32 vcc, s70, v107
	s_nop 1
	v_cndmask_b32_e32 v107, v107, v108, vcc
	v_sqrt_f32_e32 v108, v107
	s_nop 0
	v_add_u32_e32 v109, -1, v108
	v_fma_f32 v110, -v109, v108, v107
	v_cmp_ge_f32_e64 s[16:17], 0, v110
	v_add_u32_e32 v110, 1, v108
	s_nop 0
	v_cndmask_b32_e64 v109, v108, v109, s[16:17]
	v_fma_f32 v108, -v110, v108, v107
	v_cmp_lt_f32_e64 s[16:17], 0, v108
	s_nop 1
	v_cndmask_b32_e64 v108, v109, v110, s[16:17]
	v_mul_f32_e32 v109, 0x37800000, v108
	v_cndmask_b32_e32 v108, v108, v109, vcc
	v_cmp_class_f32_e32 vcc, v107, v187
	s_nop 1
	v_cndmask_b32_e32 v107, v108, v107, vcc
	v_div_scale_f32 v108, s[2:3], v107, v107, 1.0
	v_rcp_f32_e32 v109, v108
	s_nop 0
	v_fma_f32 v110, -v108, v109, 1.0
	v_fmac_f32_e32 v109, v110, v109
	v_div_scale_f32 v110, vcc, 1.0, v107, 1.0
	v_mul_f32_e32 v111, v110, v109
	v_fma_f32 v112, -v108, v111, v110
	v_fmac_f32_e32 v111, v112, v109
	v_fma_f32 v108, -v108, v111, v110
	v_div_fmas_f32 v108, v108, v109, v111
	v_div_fixup_f32 v108, v108, v107, 1.0
	v_pk_mul_f32 v[102:103], v[102:103], v[108:109] op_sel_hi:[1,0]
	v_pk_mul_f32 v[104:105], v[104:105], v[108:109] op_sel_hi:[1,0]
	v_pk_mul_f32 v[98:99], v[98:99], v[108:109] op_sel_hi:[1,0]
	v_pk_mul_f32 v[100:101], v[100:101], v[108:109] op_sel_hi:[1,0]
	v_pk_mul_f32 v[78:79], v[78:79], v[108:109] op_sel_hi:[1,0]
	v_pk_mul_f32 v[80:81], v[80:81], v[108:109] op_sel_hi:[1,0]
	v_pk_mul_f32 v[74:75], v[74:75], v[108:109] op_sel_hi:[1,0]
	v_pk_mul_f32 v[76:77], v[76:77], v[108:109] op_sel_hi:[1,0]
	v_pk_mul_f32 v[104:105], v[88:89], v[104:105]
	v_pk_mul_f32 v[102:103], v[86:87], v[102:103]
	v_pk_mul_f32 v[100:101], v[84:85], v[100:101]
	v_pk_mul_f32 v[98:99], v[82:83], v[98:99]
	v_pk_mul_f32 v[80:81], v[96:97], v[80:81]
	v_pk_mul_f32 v[78:79], v[94:95], v[78:79]
	v_pk_mul_f32 v[76:77], v[92:93], v[76:77]
	v_pk_mul_f32 v[74:75], v[90:91], v[74:75]
	s_and_b64 vcc, exec, s[14:15]
	s_cbranch_vccz .LBB0_2968

.LBB0_2949:
	v_mov_b32_e32 v108, v182
	v_mov_b32_e32 v109, v182
	v_pk_mul_f32 v[102:103], v[182:183], v[102:103]
	v_pk_mul_f32 v[110:111], v[108:109], v[100:101]
	v_pk_mul_f32 v[100:101], v[182:183], v[98:99]
	v_cvt_pk_bf16_f32 v98, v102, v103
	v_mov_b64_e32 v[102:103], s[22:23]
	v_mad_i64_i32 v[102:103], s[2:3], v106, s72, v[102:103]
	v_lshl_add_u64 v[102:103], s[0:1], 1, v[102:103]
	v_pk_mul_f32 v[104:105], v[108:109], v[104:105]
	v_lshl_add_u64 v[102:103], v[102:103], 0, v[162:163]
	v_cvt_pk_bf16_f32 v99, v104, v105
	v_cvt_pk_bf16_f32 v100, v100, v101
	v_cvt_pk_bf16_f32 v101, v110, v111
	global_store_dwordx4 v[102:103], v[98:101], off
	v_pk_mul_f32 v[80:81], v[108:109], v[80:81]
	v_pk_mul_f32 v[78:79], v[182:183], v[78:79]
	v_pk_mul_f32 v[98:99], v[108:109], v[76:77]
	v_pk_mul_f32 v[76:77], v[182:183], v[74:75]
	v_cvt_pk_bf16_f32 v74, v78, v79
	v_cvt_pk_bf16_f32 v75, v80, v81
	s_nop 0
	v_cvt_pk_bf16_f32 v76, v76, v77
	v_cvt_pk_bf16_f32 v77, v98, v99
	v_add_u32_e32 v98, 0xb0, v180
	v_ashrrev_i32_e32 v99, 31, v98
	global_store_dwordx4 v[102:103], v[74:77], off offset:64
	s_nop 1
	v_lshlrev_b64 v[74:75], 6, v[98:99]
	v_lshl_add_u64 v[104:105], s[36:37], 0, v[74:75]
	global_load_dwordx4 v[74:77], v[104:105], off
	global_load_dwordx4 v[78:81], v[104:105], off offset:16
	global_load_dwordx4 v[100:103], v[104:105], off offset:32
	s_nop 0
	global_load_dwordx4 v[104:107], v[104:105], off offset:48
	s_waitcnt vmcnt(3)
	v_mov_b32_e32 v108, v75
	v_mov_b32_e32 v109, v76
	v_mov_b32_e32 v75, v77
	s_waitcnt vmcnt(2)
	v_mov_b32_e32 v76, v79
	v_mov_b32_e32 v77, v80
	v_mov_b32_e32 v79, v81
	v_pk_add_f32 v[74:75], v[108:109], v[74:75]
	v_pk_add_f32 v[76:77], v[76:77], v[78:79]
	v_pk_add_f32 v[74:75], v[74:75], v[74:75] op_sel:[0,1] op_sel_hi:[1,0]
	v_pk_add_f32 v[76:77], v[76:77], v[76:77] op_sel:[0,1] op_sel_hi:[1,0]
	s_waitcnt vmcnt(1)
	v_add_f32_e32 v80, v100, v101
	v_add_f32_e32 v100, v102, v103
	s_waitcnt vmcnt(0)
	v_mov_b32_e32 v81, v106
	v_mov_b32_e32 v101, v107
	v_mov_b32_e32 v75, v104
	v_mov_b32_e32 v77, v105
	v_pk_add_f32 v[78:79], v[80:81], v[100:101]
	v_pk_add_f32 v[74:75], v[74:75], v[76:77]
	s_nop 0
	v_pk_add_f32 v[74:75], v[74:75], v[78:79]
	s_nop 0
	v_add_f32_e32 v74, v74, v75
	v_fmamk_f32 v74, v74, 0x3a800000, v186
	v_mul_f32_e32 v75, 0x4f800000, v74
	v_cmp_gt_f32_e32 vcc, s70, v74
	s_nop 1
	v_cndmask_b32_e32 v74, v74, v75, vcc
	v_sqrt_f32_e32 v75, v74
	s_nop 0
	v_add_u32_e32 v76, -1, v75
	v_add_u32_e32 v77, 1, v75
	v_fma_f32 v78, -v76, v75, v74
	v_fma_f32 v79, -v77, v75, v74
	v_cmp_ge_f32_e64 s[16:17], 0, v78
	s_nop 1
	v_cndmask_b32_e64 v75, v75, v76, s[16:17]
	v_cmp_lt_f32_e64 s[16:17], 0, v79
	s_nop 1
	v_cndmask_b32_e64 v75, v75, v77, s[16:17]
	v_mul_f32_e32 v76, 0x37800000, v75
	v_cndmask_b32_e32 v75, v75, v76, vcc
	v_cmp_class_f32_e32 vcc, v74, v187
	s_nop 1
	v_cndmask_b32_e32 v74, v75, v74, vcc
	v_div_scale_f32 v75, s[2:3], v74, v74, 1.0
	v_rcp_f32_e32 v76, v75
	v_div_scale_f32 v77, vcc, 1.0, v74, 1.0
	v_fma_f32 v78, -v75, v76, 1.0
	v_fmac_f32_e32 v76, v78, v76
	v_mul_f32_e32 v78, v77, v76
	v_fma_f32 v79, -v75, v78, v77
	v_fmac_f32_e32 v78, v79, v76
	v_fma_f32 v75, -v75, v78, v77
	v_div_fmas_f32 v75, v75, v76, v78
	v_div_fixup_f32 v100, v75, v74, 1.0
	s_and_b64 vcc, exec, s[10:11]
	v_pk_mul_f32 v[80:81], v[8:9], v[100:101] op_sel_hi:[1,0]
	v_pk_mul_f32 v[78:79], v[6:7], v[100:101] op_sel_hi:[1,0]
	v_pk_mul_f32 v[76:77], v[4:5], v[100:101] op_sel_hi:[1,0]
	v_pk_mul_f32 v[74:75], v[2:3], v[100:101] op_sel_hi:[1,0]
	v_pk_mul_f32 v[72:73], v[72:73], v[100:101] op_sel_hi:[1,0]
	v_pk_mul_f32 v[70:71], v[70:71], v[100:101] op_sel_hi:[1,0]
	v_pk_mul_f32 v[68:69], v[68:69], v[100:101] op_sel_hi:[1,0]
	v_pk_mul_f32 v[66:67], v[66:67], v[100:101] op_sel_hi:[1,0]
	s_cbranch_vccnz .LBB0_2969
	v_pk_mul_f32 v[100:101], v[80:81], v[80:81]
	v_pk_mul_f32 v[102:103], v[78:79], v[78:79]
	s_nop 0
	v_pk_mov_b32 v[104:105], v[102:103], v[100:101] op_sel:[1,0]
	v_mov_b32_e32 v103, v101
	v_pk_add_f32 v[100:101], v[104:105], v[102:103]
	v_pk_mul_f32 v[102:103], v[76:77], v[76:77]
	v_pk_add_f32 v[100:101], v[100:101], v[100:101] op_sel_hi:[0,1]
	v_pk_mul_f32 v[104:105], v[74:75], v[74:75]
	v_mul_f32_e32 v100, v70, v70
	v_pk_mov_b32 v[106:107], v[104:105], v[102:103] op_sel:[1,0]
	v_mov_b32_e32 v105, v103
	v_pk_add_f32 v[102:103], v[106:107], v[104:105]
	v_pk_fma_f32 v[104:105], v[70:71], v[70:71], v[100:101] op_sel_hi:[1,1,0]
	v_mul_f32_e32 v100, v72, v72
	v_pk_add_f32 v[102:103], v[102:103], v[102:103] op_sel_hi:[0,1]
	v_pk_fma_f32 v[106:107], v[72:73], v[72:73], v[100:101] op_sel_hi:[1,1,0]
	v_mul_f32_e32 v104, v66, v66
	v_mul_f32_e32 v106, v67, v67
	v_mul_f32_e32 v100, v68, v68
	v_mul_f32_e32 v102, v69, v69
	v_pk_add_f32 v[104:105], v[104:105], v[106:107]
	v_pk_add_f32 v[100:101], v[100:101], v[102:103]
	s_nop 0
	v_pk_add_f32 v[100:101], v[104:105], v[100:101]
	s_nop 0
	v_add_f32_e32 v99, v100, v101
	v_and_b32_e32 v101, 64, v191
	v_xor_b32_e32 v100, 16, v191
	v_add_u32_e32 v101, 64, v101
	v_cmp_lt_i32_e32 vcc, v100, v101
	s_nop 1
	v_cndmask_b32_e32 v100, v191, v100, vcc
	v_lshlrev_b32_e32 v100, 2, v100
	ds_bpermute_b32 v100, v100, v99
	s_waitcnt lgkmcnt(0)
	v_add_f32_e32 v99, v99, v100
	v_xor_b32_e32 v100, 32, v191
	v_cmp_lt_i32_e32 vcc, v100, v101
	s_nop 1
	v_cndmask_b32_e32 v100, v191, v100, vcc
	v_lshlrev_b32_e32 v100, 2, v100
	ds_bpermute_b32 v100, v100, v99
	s_waitcnt lgkmcnt(0)
	v_add_f32_e32 v99, v99, v100
	v_fmamk_f32 v99, v99, 0x3c800000, v186
	v_mul_f32_e32 v100, 0x4f800000, v99
	v_cmp_gt_f32_e32 vcc, s70, v99
	s_nop 1
	v_cndmask_b32_e32 v99, v99, v100, vcc
	v_sqrt_f32_e32 v100, v99
	s_nop 0
	v_add_u32_e32 v101, -1, v100
	v_fma_f32 v102, -v101, v100, v99
	v_cmp_ge_f32_e64 s[10:11], 0, v102
	v_add_u32_e32 v102, 1, v100
	s_nop 0
	v_cndmask_b32_e64 v101, v100, v101, s[10:11]
	v_fma_f32 v100, -v102, v100, v99
	v_cmp_lt_f32_e64 s[10:11], 0, v100
	s_nop 1
	v_cndmask_b32_e64 v100, v101, v102, s[10:11]
	v_mul_f32_e32 v101, 0x37800000, v100
	v_cndmask_b32_e32 v100, v100, v101, vcc
	v_cmp_class_f32_e32 vcc, v99, v187
	s_nop 1
	v_cndmask_b32_e32 v99, v100, v99, vcc
	v_div_scale_f32 v100, s[2:3], v99, v99, 1.0
	v_rcp_f32_e32 v101, v100
	s_nop 0
	v_fma_f32 v102, -v100, v101, 1.0
	v_fmac_f32_e32 v101, v102, v101
	v_div_scale_f32 v102, vcc, 1.0, v99, 1.0
	v_mul_f32_e32 v103, v102, v101
	v_fma_f32 v104, -v100, v103, v102
	v_fmac_f32_e32 v103, v104, v101
	v_fma_f32 v100, -v100, v103, v102
	v_div_fmas_f32 v100, v100, v101, v103
	v_div_fixup_f32 v100, v100, v99, 1.0
	v_pk_mul_f32 v[78:79], v[78:79], v[100:101] op_sel_hi:[1,0]
	v_pk_mul_f32 v[80:81], v[80:81], v[100:101] op_sel_hi:[1,0]
	v_pk_mul_f32 v[74:75], v[74:75], v[100:101] op_sel_hi:[1,0]
	v_pk_mul_f32 v[76:77], v[76:77], v[100:101] op_sel_hi:[1,0]
	v_pk_mul_f32 v[70:71], v[70:71], v[100:101] op_sel_hi:[1,0]
	v_pk_mul_f32 v[72:73], v[72:73], v[100:101] op_sel_hi:[1,0]
	v_pk_mul_f32 v[66:67], v[66:67], v[100:101] op_sel_hi:[1,0]
	v_pk_mul_f32 v[68:69], v[68:69], v[100:101] op_sel_hi:[1,0]
	v_pk_mul_f32 v[80:81], v[88:89], v[80:81]
	v_pk_mul_f32 v[78:79], v[86:87], v[78:79]
	v_pk_mul_f32 v[76:77], v[84:85], v[76:77]
	v_pk_mul_f32 v[74:75], v[82:83], v[74:75]
	v_pk_mul_f32 v[72:73], v[96:97], v[72:73]
	v_pk_mul_f32 v[70:71], v[94:95], v[70:71]
	v_pk_mul_f32 v[68:69], v[92:93], v[68:69]
	v_pk_mul_f32 v[66:67], v[90:91], v[66:67]
	s_and_b64 vcc, exec, s[14:15]
	s_cbranch_vccz .LBB0_2970

.LBB0_2953:
	v_mov_b32_e32 v82, v182
	v_mov_b32_e32 v83, v182
	v_pk_mul_f32 v[78:79], v[182:183], v[78:79]
	v_pk_mul_f32 v[84:85], v[82:83], v[76:77]
	v_pk_mul_f32 v[76:77], v[182:183], v[74:75]
	v_cvt_pk_bf16_f32 v74, v78, v79
	v_mov_b64_e32 v[78:79], s[22:23]
	v_mad_i64_i32 v[78:79], s[2:3], v98, s72, v[78:79]
	v_lshl_add_u64 v[78:79], s[0:1], 1, v[78:79]
	v_pk_mul_f32 v[80:81], v[82:83], v[80:81]
	v_lshl_add_u64 v[78:79], v[78:79], 0, v[162:163]
	v_cvt_pk_bf16_f32 v75, v80, v81
	v_cvt_pk_bf16_f32 v76, v76, v77
	v_cvt_pk_bf16_f32 v77, v84, v85
	global_store_dwordx4 v[78:79], v[74:77], off
	v_pk_mul_f32 v[72:73], v[82:83], v[72:73]
	s_nop 0
	v_pk_mul_f32 v[74:75], v[82:83], v[68:69]
	v_pk_mul_f32 v[68:69], v[182:183], v[66:67]
	v_pk_mul_f32 v[70:71], v[182:183], v[70:71]
	s_nop 0
	v_cvt_pk_bf16_f32 v66, v70, v71
	v_cvt_pk_bf16_f32 v67, v72, v73
	v_cvt_pk_bf16_f32 v68, v68, v69
	v_cvt_pk_bf16_f32 v69, v74, v75
	global_store_dwordx4 v[78:79], v[66:69], off offset:64
